# v2 + phase-0 mod rows read with sc1 loads, L1 invalidate after the mod publication wait dropped; also: barrier per-XCD count load hoisted before the arrival atomic
# speedup vs baseline: 1.0095x; 1.0021x over previous
; #define LAS __attribute__((address_space(3)))
; #define GAS __attribute__((address_space(1)))
; __device__ __forceinline__ unsigned xb_ld(unsigned* p)              { return __hip_atomic_load(p, __ATOMIC_RELAXED, __HIP_MEMORY_SCOPE_AGENT); }
; #define XB_SPIN(cond, bar) do { unsigned _sp = 0; while (cond) { __builtin_amdgcn_s_sleep(1); \
;     if ((++_sp & 255u) == 0u) { if (xb_ld(&(bar)[XB_TMO])) break; if (_sp > XB_SPIN_CAP) { atomicAdd(&(bar)[XB_TMO], 1u); break; } } } } while (0)
; __device__ __forceinline__ void mod_wait(Frame& F) {
;     if (F.tid == 0) { unsigned* ctl = (unsigned*)(F.ws + WS_CTL); unsigned* bar = ctl + CW_BAR;
;         XB_SPIN(xb_ld(ctl + CW_MODCNT) < (unsigned)F.G, bar);
;         __builtin_amdgcn_fence(__ATOMIC_ACQUIRE, "agent"); }
;     __syncthreads();
; __device__ __forceinline__ void normmod_row(const float* xrow, const float* nw, const float* sh, const float* sc, int lane, f32x4 (&v)[4]) {
;     const GAS f32x4* xr = (const GAS f32x4*)xrow + lane; float s = 0.f;
; #pragma unroll
;     for (int j = 0; j < 4; ++j) { v[j] = __builtin_nontemporal_load(xr + 64 * j); s += (v[j].x * v[j].x + v[j].y * v[j].y) + (v[j].z * v[j].z + v[j].w * v[j].w); }
;     const float rstd = 1.0f / sqrtf(wave_sum(s) * (1.f / D) + EPS);
; #pragma unroll
;     for (int j = 0; j < 4; ++j) { const f32x4 w = ((const GAS f32x4*)nw)[lane + 64 * j]; v[j] = v[j] * rstd * w;
;         if (sc) { const f32x4 a = ((const GAS f32x4*)sc)[lane + 64 * j], b = ((const GAS f32x4*)sh)[lane + 64 * j]; v[j] = v[j] * (1.f + a) + b; } }
; }
; __device__ __forceinline__ void phase_upass(Frame& F) {
;     const float* x = F.in[0]; const float* nw = F.in[4]; const float* mod = (const float*)(F.ws + WS_MOD); bf16_t* UAUG = (bf16_t*)(F.ws + WS_UAUG);
;     LAS bf16_t* tl = (LAS bf16_t*)(F.lds + F.wave * 8192);
;     const int gw = F.bid * NWAVES + F.wave, NGW = F.G * NWAVES;
;     for (int q4 = gw; q4 < T / 4; q4 += NGW) {
;         const int m0 = q4 * 4, b = m0 / SEQ, tt = m0 % SEQ, c = tt / QC, s0 = tt % QC; const float* mb = mod + (size_t)b * 6 * D;
; #pragma unroll
;         for (int t = 0; t < 4; ++t) { f32x4 v[4]; normmod_row(x + (size_t)(m0 + t) * D, nw, mb, mb + D, F.lane, v);
.LBB0_275:
	s_waitcnt vmcnt(0)
.LBB0_276:
	s_or_b64 exec, exec, s[0:1]
	s_add_i32 s17, s17, s3
	s_cmpk_gt_i32 s17, 0xfff
	s_barrier
	s_cbranch_scc1 .LBB0_279
	v_and_b32_e32 v0, 64, v120
	v_add_u32_e32 v0, 64, v0
	v_xor_b32_e32 v1, 1, v120
	v_cmp_lt_i32_e32 vcc, v1, v0
	s_add_u32 s18, s34, 0x4000000
	s_addc_u32 s19, s35, 0
	v_cndmask_b32_e32 v1, v120, v1, vcc
	v_lshlrev_b32_e32 v152, 2, v1
	v_xor_b32_e32 v1, 2, v120
	v_cmp_lt_i32_e32 vcc, v1, v0
	s_lshl_b32 s0, s3, 13
	s_add_i32 s0, s0, 0
	v_cndmask_b32_e32 v1, v120, v1, vcc
	v_lshlrev_b32_e32 v153, 2, v1
	v_xor_b32_e32 v1, 4, v120
	v_cmp_lt_i32_e32 vcc, v1, v0
	v_bfe_u32 v158, v120, 1, 2
	v_lshlrev_b32_e32 v2, 5, v32
	v_cndmask_b32_e32 v1, v120, v1, vcc
	v_lshlrev_b32_e32 v154, 2, v1
	v_xor_b32_e32 v1, 8, v120
	v_cmp_lt_i32_e32 vcc, v1, v0
	v_readlane_b32 s36, v252, 2
	v_readlane_b32 s44, v252, 10
	v_cndmask_b32_e32 v1, v120, v1, vcc
	v_lshlrev_b32_e32 v155, 2, v1
	v_xor_b32_e32 v1, 16, v120
	v_cmp_lt_i32_e32 vcc, v1, v0
	v_readlane_b32 s45, v252, 11
	v_readlane_b32 s37, v252, 3
	v_cndmask_b32_e32 v1, v120, v1, vcc
	v_lshlrev_b32_e32 v156, 2, v1
	v_xor_b32_e32 v1, 32, v120
	v_cmp_lt_i32_e32 vcc, v1, v0
	v_readlane_b32 s46, v252, 12
	v_readlane_b32 s47, v252, 13
	v_cndmask_b32_e32 v0, v120, v1, vcc
	v_lshlrev_b32_e32 v157, 2, v0
	v_and_b32_e32 v0, 8, v121
	v_lshl_add_u32 v1, v158, 11, s0
	v_lshlrev_b32_e32 v3, 1, v0
	v_add3_u32 v159, v1, v2, v3
	v_add_u32_e32 v2, 8, v32
	v_lshlrev_b32_e32 v4, 5, v2
	v_lshlrev_b32_e32 v106, 10, v2
	v_or_b32_e32 v2, 16, v32
	v_add3_u32 v160, v1, v4, v3
	v_lshlrev_b32_e32 v4, 5, v2
	v_lshlrev_b32_e32 v108, 10, v2
	v_add_u32_e32 v2, 24, v32
	v_add3_u32 v161, v1, v4, v3
	v_lshlrev_b32_e32 v4, 5, v2
	v_lshlrev_b32_e32 v110, 10, v2
	v_or_b32_e32 v2, 32, v32
	v_add3_u32 v162, v1, v4, v3
	v_lshlrev_b32_e32 v4, 5, v2
	v_lshlrev_b32_e32 v112, 10, v2
	v_add_u32_e32 v2, 40, v32
	v_add3_u32 v163, v1, v4, v3
	v_lshlrev_b32_e32 v4, 5, v2
	v_lshlrev_b32_e32 v114, 10, v2
	v_or_b32_e32 v2, 48, v32
	v_readlane_b32 s48, v252, 14
	v_readlane_b32 s49, v252, 15
	v_readlane_b32 s50, v252, 16
	v_readlane_b32 s51, v252, 17
	s_mov_b64 s[20:21], s[44:45]
	v_add3_u32 v164, v1, v4, v3
	v_lshlrev_b32_e32 v4, 5, v2
	v_lshlrev_b32_e32 v116, 10, v2
	v_add_u32_e32 v2, 56, v32
	v_mov_b32_e32 v101, 0
	s_mov_b64 s[22:23], s[46:47]
	s_mov_b64 s[24:25], s[48:49]
	s_mov_b64 s[26:27], s[50:51]
	s_mov_b64 s[12:13], s[36:37]
	v_add3_u32 v165, v1, v4, v3
	v_lshlrev_b32_e32 v4, 5, v2
	s_lshl_b32 s1, s2, 5
	s_lshl_b32 s4, s3, 2
	v_lshl_add_u64 v[102:103], s[20:21], 0, v[100:101]
	v_lshlrev_b32_e32 v104, 10, v32
	v_mov_b32_e32 v105, v101
	v_mov_b32_e32 v107, v101
	v_mov_b32_e32 v109, v101
	v_mov_b32_e32 v111, v101
	v_mov_b32_e32 v113, v101
	v_mov_b32_e32 v115, v101
	v_mov_b32_e32 v117, v101
	v_add3_u32 v166, v1, v4, v3
	v_lshlrev_b32_e32 v118, 10, v2
	v_mov_b32_e32 v119, v101
	v_lshl_add_u64 v[122:123], s[12:13], 0, v[100:101]
	s_add_i32 s20, s1, s4
	s_lshl_b32 s24, s33, 5
	v_mov_b32_e32 v167, 0x358637bd
	s_mov_b32 s25, 0xf800000
	v_mov_b32_e32 v168, 0x260
	v_lshlrev_b32_e32 v100, 4, v120
	s_mov_b64 s[22:23], 0x1000
	s_movk_i32 s26, 0x1000
	s_movk_i32 s27, 0x7fff
	s_mov_b32 s28, 0xffff0000
	s_movk_i32 s29, 0x300
	v_lshlrev_b32_e32 v120, 1, v0
	v_add_u32_e32 v169, s0, v121
	v_readlane_b32 s38, v252, 4
	v_readlane_b32 s39, v252, 5
	v_readlane_b32 s40, v252, 6
	v_readlane_b32 s41, v252, 7
	v_readlane_b32 s42, v252, 8
	v_readlane_b32 s43, v252, 9
.LBB0_278:
	s_ashr_i32 s0, s17, 31
	s_ashr_i32 s21, s20, 31
	s_lshr_b32 s0, s0, 22
	s_lshr_b32 s1, s21, 20
	s_add_i32 s0, s17, s0
	s_add_i32 s1, s20, s1
	s_ashr_i32 s5, s0, 10
	s_and_b32 s0, s1, 0xf000
	s_sub_i32 s4, s20, s0
	s_sext_i32_i16 s6, s4
	s_bfe_u32 s6, s6, 0x4001b
	s_mul_i32 s0, s5, 6
	s_add_i32 s6, s4, s6
	s_ashr_i32 s1, s0, 31
	s_sext_i32_i16 s7, s6
	s_and_b32 s6, s6, 0xfff0
	s_lshl_b64 s[0:1], s[0:1], 12
	s_lshr_b32 s30, s7, 4
	s_sub_i32 s4, s4, s6
	s_add_u32 s10, s14, s0
	s_addc_u32 s11, s15, s1
	s_sext_i32_i16 s7, s4
	s_lshl_b64 s[36:37], s[20:21], 12
	v_lshl_add_u64 v[50:51], s[10:11], 0, v[100:101]
	v_or_b32_e32 v32, s7, v158
	v_lshl_add_u64 v[40:41], v[122:123], 0, s[36:37]
	v_add_co_u32_e32 v52, vcc, s26, v50
	global_load_dwordx4 v[0:3], v[102:103], off
	global_load_dwordx4 v[12:15], v[102:103], off offset:1024
	global_load_dwordx4 v[4:7], v[102:103], off offset:2048
	global_load_dwordx4 v[8:11], v[102:103], off offset:3072
	global_load_dwordx4 v[16:19], v100, s[10:11] sc1
	global_load_dwordx4 v[20:23], v100, s[10:11] offset:1024 sc1
	global_load_dwordx4 v[24:27], v100, s[10:11] offset:2048 sc1
	global_load_dwordx4 v[28:31], v100, s[10:11] offset:3072 sc1
	v_lshlrev_b32_e32 v48, 4, v32
	global_load_dwordx4 v[32:35], v[40:41], off nt
	global_load_dwordx4 v[36:39], v[40:41], off offset:1024 nt
	global_load_dwordx4 v[44:47], v[40:41], off offset:3072 nt
	s_nop 0
	global_load_dwordx4 v[40:43], v[40:41], off offset:2048 nt
	v_addc_co_u32_e32 v53, vcc, 0, v51, vcc
	v_lshl_add_u64 v[50:51], v[50:51], 0, s[22:23]
	s_add_i32 s4, s20, 1
	s_add_i32 s6, s20, 2
	s_add_i32 s8, s20, 3
	global_load_dwordx4 v[68:71], v[50:51], off offset:1024 sc1
	global_load_dwordx4 v[146:149], v[50:51], off offset:2048 sc1
	global_load_dwordx4 v[142:145], v[52:53], off sc1
	global_load_dwordx4 v[170:173], v[50:51], off offset:3072 sc1
	s_lshl_b32 s12, s5, 8
	s_ashr_i32 s5, s4, 31
	s_ashr_i32 s7, s6, 31
	s_ashr_i32 s9, s8, 31
	s_lshl_b64 s[4:5], s[4:5], 12
	s_lshl_b64 s[6:7], s[6:7], 12
	s_lshl_b64 s[8:9], s[8:9], 12
	v_ashrrev_i32_e32 v49, 31, v48
	v_lshl_add_u64 v[60:61], v[122:123], 0, s[4:5]
	v_lshl_add_u64 v[58:59], v[122:123], 0, s[6:7]
	v_lshl_add_u64 v[56:57], v[122:123], 0, s[8:9]
; #define LAS __attribute__((address_space(3)))
; #define GAS __attribute__((address_space(1)))
; __device__ __forceinline__ void normmod_row(const float* xrow, const float* nw, const float* sh, const float* sc, int lane, f32x4 (&v)[4]) {
;     const GAS f32x4* xr = (const GAS f32x4*)xrow + lane; float s = 0.f;
; #pragma unroll
;     for (int j = 0; j < 4; ++j) { v[j] = __builtin_nontemporal_load(xr + 64 * j); s += (v[j].x * v[j].x + v[j].y * v[j].y) + (v[j].z * v[j].z + v[j].w * v[j].w); }
; __device__ __forceinline__ void phase_upass(Frame& F) {
;     ...
;         for (int i = 0; i < 8; ++i) { const int g = 8 * i + (F.lane >> 3), pc = F.lane & 7, t = pc >> 1, hf = pc & 1;
;             const u32x4 o = *(const LAS u32x4*)(tl + t * 1024 + g * 16 + hf * 8);
;             *(GAS u32x4*)(UAUG + ((size_t)g * BC + b * NCH + c) * UA + (s0 + t) * 16 + hf * 8) = o; }
	v_lshlrev_b64 v[126:127], 1, v[48:49]
	global_load_dwordx4 v[84:87], v[60:61], off nt
	global_load_dwordx4 v[88:91], v[60:61], off offset:1024 nt
	global_load_dwordx4 v[64:67], v[58:59], off nt
	global_load_dwordx4 v[72:75], v[58:59], off offset:1024 nt
	global_load_dwordx4 v[48:51], v[56:57], off nt
	global_load_dwordx4 v[52:55], v[56:57], off offset:1024 nt
	global_load_dwordx4 v[92:95], v[60:61], off offset:2048 nt
	global_load_dwordx4 v[96:99], v[60:61], off offset:3072 nt
	global_load_dwordx4 v[80:83], v[58:59], off offset:3072 nt
	global_load_dwordx4 v[76:79], v[58:59], off offset:2048 nt
	s_nop 0
	global_load_dwordx4 v[60:63], v[56:57], off offset:3072 nt
	s_nop 0
	global_load_dwordx4 v[56:59], v[56:57], off offset:2048 nt
	s_bfe_i64 s[0:1], s[30:31], 0x100000
	s_ashr_i32 s10, s12, 31
	s_add_u32 s0, s0, s12
	s_addc_u32 s1, s1, s10
	v_mov_b64_e32 v[124:125], s[18:19]
	v_lshl_add_u64 v[128:129], v[104:105], 0, s[0:1]
	v_lshl_add_u64 v[130:131], v[106:107], 0, s[0:1]
	v_lshl_add_u64 v[132:133], v[108:109], 0, s[0:1]
	v_lshl_add_u64 v[134:135], v[110:111], 0, s[0:1]
	v_lshl_add_u64 v[136:137], v[112:113], 0, s[0:1]
	v_lshl_add_u64 v[138:139], v[114:115], 0, s[0:1]
	v_lshl_add_u64 v[140:141], v[116:117], 0, s[0:1]
	v_lshl_add_u64 v[150:151], v[118:119], 0, s[0:1]
	v_mad_u64_u32 v[174:175], s[0:1], v128, s29, v[124:125]
	v_mad_u64_u32 v[176:177], s[0:1], v130, s29, v[124:125]
	v_mad_u64_u32 v[178:179], s[0:1], v132, s29, v[124:125]
	v_mad_u64_u32 v[180:181], s[0:1], v134, s29, v[124:125]
	v_mad_u64_u32 v[182:183], s[0:1], v136, s29, v[124:125]
	v_mad_u64_u32 v[184:185], s[0:1], v138, s29, v[124:125]
	v_mad_u64_u32 v[186:187], s[0:1], v140, s29, v[124:125]
	v_mad_u64_u32 v[124:125], s[0:1], v150, s29, v[124:125]
	v_mad_i32_i24 v175, v129, s29, v175
	v_mad_i32_i24 v177, v131, s29, v177
	v_mad_i32_i24 v179, v133, s29, v179
	v_mad_i32_i24 v181, v135, s29, v181
	v_mad_i32_i24 v183, v137, s29, v183
	v_mad_i32_i24 v185, v139, s29, v185
	v_mad_i32_i24 v187, v141, s29, v187
	v_mad_i32_i24 v125, v151, s29, v125
	v_mov_b32_e32 v121, v101
	v_lshl_add_u64 v[128:129], v[174:175], 0, v[126:127]
	v_lshl_add_u64 v[130:131], v[176:177], 0, v[126:127]
	v_lshl_add_u64 v[132:133], v[178:179], 0, v[126:127]
	v_lshl_add_u64 v[134:135], v[180:181], 0, v[126:127]
	v_lshl_add_u64 v[136:137], v[182:183], 0, v[126:127]
	v_lshl_add_u64 v[138:139], v[184:185], 0, v[126:127]
	v_lshl_add_u64 v[140:141], v[186:187], 0, v[126:127]
	v_lshl_add_u64 v[150:151], v[124:125], 0, v[126:127]
	v_lshl_add_u64 v[124:125], v[128:129], 0, v[120:121]
	v_lshl_add_u64 v[126:127], v[130:131], 0, v[120:121]
	v_lshl_add_u64 v[128:129], v[132:133], 0, v[120:121]
	v_lshl_add_u64 v[130:131], v[134:135], 0, v[120:121]
	v_lshl_add_u64 v[132:133], v[136:137], 0, v[120:121]
	v_lshl_add_u64 v[134:135], v[138:139], 0, v[120:121]
	v_lshl_add_u64 v[136:137], v[140:141], 0, v[120:121]
	v_lshl_add_u64 v[138:139], v[150:151], 0, v[120:121]
	s_add_i32 s17, s17, s16
	s_waitcnt vmcnt(19)
	v_pk_mul_f32 v[140:141], v[34:35], v[34:35]
	v_pk_mul_f32 v[174:175], v[32:33], v[32:33]
	s_waitcnt vmcnt(18)
	v_pk_mul_f32 v[150:151], v[38:39], v[38:39]
	v_pk_mul_f32 v[176:177], v[36:37], v[36:37]
	s_waitcnt vmcnt(16)
	v_mul_f32_e32 v178, v41, v41
	v_mul_f32_e32 v180, v43, v43
	v_pk_mov_b32 v[182:183], v[174:175], v[140:141] op_sel:[1,0]
	v_mov_b32_e32 v175, v141
	v_pk_mov_b32 v[184:185], v[176:177], v[150:151] op_sel:[1,0]
	v_mov_b32_e32 v177, v151
	v_mul_f32_e32 v121, v46, v46
	v_mul_f32_e32 v186, v47, v47
	v_pk_fma_f32 v[178:179], v[40:41], v[40:41], v[178:179] op_sel_hi:[1,1,0]
	v_pk_fma_f32 v[180:181], v[42:43], v[42:43], v[180:181] op_sel_hi:[1,1,0]
	s_waitcnt vmcnt(13)
	v_pk_add_f32 v[140:141], v[144:145], 1.0 op_sel_hi:[1,0]
	v_pk_add_f32 v[144:145], v[148:149], 1.0 op_sel_hi:[1,0]
	s_waitcnt vmcnt(12)
	v_pk_add_f32 v[148:149], v[172:173], 1.0 op_sel_hi:[1,0]
	v_pk_add_f32 v[150:151], v[170:171], 1.0 op_sel_hi:[1,0]
	v_pk_add_f32 v[170:171], v[182:183], v[174:175]
	v_pk_add_f32 v[172:173], v[184:185], v[176:177]
	v_mul_f32_e32 v213, v44, v44
	v_mul_f32_e32 v214, v45, v45
	v_mov_b32_e32 v179, v121
	v_mov_b32_e32 v181, v186
	s_waitcnt vmcnt(11)
	v_pk_mul_f32 v[174:175], v[86:87], v[86:87]
	v_pk_mul_f32 v[176:177], v[84:85], v[84:85]
	s_waitcnt vmcnt(10)
	v_pk_mul_f32 v[182:183], v[90:91], v[90:91]
	v_pk_mul_f32 v[184:185], v[88:89], v[88:89]
	s_waitcnt vmcnt(9)
	v_pk_mul_f32 v[186:187], v[66:67], v[66:67]
	v_pk_mul_f32 v[188:189], v[64:65], v[64:65]
	s_waitcnt vmcnt(8)
	v_pk_mul_f32 v[190:191], v[74:75], v[74:75]
	v_pk_mul_f32 v[192:193], v[72:73], v[72:73]
	v_pk_add_f32 v[170:171], v[170:171], v[170:171] op_sel:[0,1] op_sel_hi:[1,0]
	v_pk_add_f32 v[172:173], v[172:173], v[172:173] op_sel:[0,1] op_sel_hi:[1,0]
	s_waitcnt vmcnt(7)
	v_pk_mul_f32 v[194:195], v[50:51], v[50:51]
	v_pk_mul_f32 v[196:197], v[48:49], v[48:49]
	s_waitcnt vmcnt(6)
	v_pk_mul_f32 v[198:199], v[54:55], v[54:55]
	v_pk_mul_f32 v[200:201], v[52:53], v[52:53]
	v_pk_add_f32 v[178:179], v[178:179], v[180:181]
	v_pk_mov_b32 v[180:181], v[176:177], v[174:175] op_sel:[1,0]
	v_mov_b32_e32 v177, v175
	v_pk_mov_b32 v[174:175], v[184:185], v[182:183] op_sel:[1,0]
	v_mov_b32_e32 v185, v183
	v_pk_mov_b32 v[182:183], v[188:189], v[186:187] op_sel:[1,0]
	v_mov_b32_e32 v189, v187
	v_pk_mov_b32 v[186:187], v[192:193], v[190:191] op_sel:[1,0]
	v_mov_b32_e32 v193, v191
	v_mov_b32_e32 v171, v213
	v_mov_b32_e32 v173, v214
	s_waitcnt vmcnt(5)
; __device__ __forceinline__ float wave_sum(float v) {
; #pragma unroll
;     for (int o = 1; o < 64; o <<= 1) v += __shfl_xor(v, o);
;     return v;
; }
; __device__ __forceinline__ void normmod_row(const float* xrow, const float* nw, const float* sh, const float* sc, int lane, f32x4 (&v)[4]) {
;     ...
;     for (int j = 0; j < 4; ++j) { v[j] = __builtin_nontemporal_load(xr + 64 * j); s += (v[j].x * v[j].x + v[j].y * v[j].y) + (v[j].z * v[j].z + v[j].w * v[j].w); }
;     const float rstd = 1.0f / sqrtf(wave_sum(s) * (1.f / D) + EPS);
	v_mul_f32_e32 v202, v93, v93
	v_mul_f32_e32 v204, v95, v95
	v_pk_mov_b32 v[190:191], v[196:197], v[194:195] op_sel:[1,0]
	v_mov_b32_e32 v197, v195
	v_pk_mov_b32 v[194:195], v[200:201], v[198:199] op_sel:[1,0]
	v_mov_b32_e32 v201, v199
	v_pk_add_f32 v[176:177], v[180:181], v[176:177]
	v_pk_add_f32 v[174:175], v[174:175], v[184:185]
	v_pk_add_f32 v[180:181], v[182:183], v[188:189]
	v_pk_add_f32 v[182:183], v[186:187], v[192:193]
	v_pk_add_f32 v[170:171], v[170:171], v[172:173]
	s_waitcnt vmcnt(4)
	v_mul_f32_e32 v121, v98, v98
	v_mul_f32_e32 v215, v99, v99
	s_waitcnt vmcnt(2)
	v_mul_f32_e32 v206, v77, v77
	v_mul_f32_e32 v208, v79, v79
	s_waitcnt vmcnt(0)
	v_mul_f32_e32 v210, v57, v57
	v_mul_f32_e32 v212, v59, v59
	v_mul_f32_e32 v220, v96, v96
	v_mul_f32_e32 v221, v97, v97
	v_mul_f32_e32 v222, v80, v80
	v_mul_f32_e32 v223, v81, v81
	v_pk_fma_f32 v[198:199], v[92:93], v[92:93], v[202:203] op_sel_hi:[1,1,0]
	v_pk_fma_f32 v[202:203], v[94:95], v[94:95], v[204:205] op_sel_hi:[1,1,0]
	v_pk_add_f32 v[184:185], v[190:191], v[196:197]
	v_pk_add_f32 v[186:187], v[194:195], v[200:201]
	v_pk_add_f32 v[176:177], v[176:177], v[176:177] op_sel:[0,1] op_sel_hi:[1,0]
	v_pk_add_f32 v[174:175], v[174:175], v[174:175] op_sel:[0,1] op_sel_hi:[1,0]
	v_pk_add_f32 v[180:181], v[180:181], v[180:181] op_sel:[0,1] op_sel_hi:[1,0]
	v_pk_add_f32 v[182:183], v[182:183], v[182:183] op_sel:[0,1] op_sel_hi:[1,0]
	v_pk_add_f32 v[170:171], v[170:171], v[178:179]
	v_mul_f32_e32 v216, v82, v82
	v_mul_f32_e32 v217, v83, v83
	v_mul_f32_e32 v218, v62, v62
	v_mul_f32_e32 v219, v63, v63
	v_mul_f32_e32 v224, v60, v60
	v_mul_f32_e32 v225, v61, v61
	v_pk_fma_f32 v[204:205], v[76:77], v[76:77], v[206:207] op_sel_hi:[1,1,0]
	v_pk_fma_f32 v[206:207], v[78:79], v[78:79], v[208:209] op_sel_hi:[1,1,0]
	v_pk_fma_f32 v[208:209], v[56:57], v[56:57], v[210:211] op_sel_hi:[1,1,0]
	v_pk_fma_f32 v[210:211], v[58:59], v[58:59], v[212:213] op_sel_hi:[1,1,0]
	v_mov_b32_e32 v199, v121
	v_mov_b32_e32 v203, v215
	v_pk_add_f32 v[184:185], v[184:185], v[184:185] op_sel:[0,1] op_sel_hi:[1,0]
	v_pk_add_f32 v[186:187], v[186:187], v[186:187] op_sel:[0,1] op_sel_hi:[1,0]
	v_mov_b32_e32 v177, v220
	v_mov_b32_e32 v175, v221
	v_mov_b32_e32 v181, v222
	v_mov_b32_e32 v183, v223
	v_add_f32_e32 v121, v170, v171
	v_mov_b32_e32 v205, v216
	v_mov_b32_e32 v207, v217
	v_mov_b32_e32 v209, v218
	v_mov_b32_e32 v211, v219
	v_pk_add_f32 v[172:173], v[198:199], v[202:203]
	v_mov_b32_e32 v185, v224
	v_mov_b32_e32 v187, v225
	v_pk_add_f32 v[174:175], v[176:177], v[174:175]
	v_pk_add_f32 v[176:177], v[180:181], v[182:183]
	ds_bpermute_b32 v180, v152, v121
	v_pk_add_f32 v[188:189], v[204:205], v[206:207]
	v_pk_add_f32 v[190:191], v[208:209], v[210:211]
	v_pk_add_f32 v[178:179], v[184:185], v[186:187]
	v_pk_add_f32 v[170:171], v[174:175], v[172:173]
	v_pk_add_f32 v[172:173], v[176:177], v[188:189]
	v_pk_add_f32 v[174:175], v[178:179], v[190:191]
	v_add_f32_e32 v170, v170, v171
	v_add_f32_e32 v171, v172, v173
	v_add_f32_e32 v172, v174, v175
	ds_bpermute_b32 v173, v152, v170
	ds_bpermute_b32 v174, v152, v171
	ds_bpermute_b32 v175, v152, v172
	s_waitcnt lgkmcnt(3)
	v_add_f32_e32 v121, v121, v180
	ds_bpermute_b32 v176, v153, v121
	s_waitcnt lgkmcnt(3)
	v_add_f32_e32 v170, v170, v173
	s_waitcnt lgkmcnt(2)
	v_add_f32_e32 v171, v171, v174
	s_waitcnt lgkmcnt(1)
	v_add_f32_e32 v172, v172, v175
	ds_bpermute_b32 v173, v153, v170
	ds_bpermute_b32 v174, v153, v171
	ds_bpermute_b32 v175, v153, v172
	s_waitcnt lgkmcnt(3)
	v_add_f32_e32 v121, v121, v176
	ds_bpermute_b32 v176, v154, v121
	s_waitcnt lgkmcnt(3)
	v_add_f32_e32 v170, v170, v173
	s_waitcnt lgkmcnt(2)
	v_add_f32_e32 v171, v171, v174
	s_waitcnt lgkmcnt(1)
	v_add_f32_e32 v172, v172, v175
	ds_bpermute_b32 v173, v154, v170
	ds_bpermute_b32 v174, v154, v171
	ds_bpermute_b32 v175, v154, v172
	s_waitcnt lgkmcnt(3)
	v_add_f32_e32 v121, v121, v176
	ds_bpermute_b32 v176, v155, v121
	s_waitcnt lgkmcnt(3)
	v_add_f32_e32 v170, v170, v173
	s_waitcnt lgkmcnt(2)
	v_add_f32_e32 v171, v171, v174
	s_waitcnt lgkmcnt(1)
	v_add_f32_e32 v172, v172, v175
	ds_bpermute_b32 v173, v155, v170
	ds_bpermute_b32 v174, v155, v171
	ds_bpermute_b32 v175, v155, v172
	s_waitcnt lgkmcnt(3)
	v_add_f32_e32 v121, v121, v176
	ds_bpermute_b32 v176, v156, v121
	s_waitcnt lgkmcnt(3)
	v_add_f32_e32 v170, v170, v173
	s_waitcnt lgkmcnt(2)
	v_add_f32_e32 v171, v171, v174
	s_waitcnt lgkmcnt(1)
	v_add_f32_e32 v172, v172, v175
	ds_bpermute_b32 v173, v156, v170
	ds_bpermute_b32 v174, v156, v171
	ds_bpermute_b32 v175, v156, v172
	s_waitcnt lgkmcnt(3)
	v_add_f32_e32 v121, v121, v176
	ds_bpermute_b32 v176, v157, v121
	s_waitcnt lgkmcnt(3)
	v_add_f32_e32 v170, v170, v173
	s_waitcnt lgkmcnt(2)
	v_add_f32_e32 v171, v171, v174
	s_waitcnt lgkmcnt(1)
	v_add_f32_e32 v172, v172, v175
	ds_bpermute_b32 v173, v157, v170
	ds_bpermute_b32 v174, v157, v171
	ds_bpermute_b32 v175, v157, v172
	s_waitcnt lgkmcnt(3)
	v_add_f32_e32 v121, v121, v176
	v_fmamk_f32 v121, v121, 0x3a800000, v167
	v_mul_f32_e32 v176, 0x4f800000, v121
	v_cmp_gt_f32_e32 vcc, s25, v121
	s_waitcnt lgkmcnt(2)
	v_add_f32_e32 v170, v170, v173
	s_waitcnt lgkmcnt(1)
	v_add_f32_e32 v171, v171, v174
	v_cndmask_b32_e32 v121, v121, v176, vcc
	s_waitcnt lgkmcnt(0)
; #define GAS __attribute__((address_space(1)))
; __device__ __forceinline__ void normmod_row(const float* xrow, const float* nw, const float* sh, const float* sc, int lane, f32x4 (&v)[4]) {
;     ...
;     const float rstd = 1.0f / sqrtf(wave_sum(s) * (1.f / D) + EPS);
; #pragma unroll
;     for (int j = 0; j < 4; ++j) { const f32x4 w = ((const GAS f32x4*)nw)[lane + 64 * j]; v[j] = v[j] * rstd * w;
;         if (sc) { const f32x4 a = ((const GAS f32x4*)sc)[lane + 64 * j], b = ((const GAS f32x4*)sh)[lane + 64 * j]; v[j] = v[j] * (1.f + a) + b; } }
	v_add_f32_e32 v172, v172, v175
	v_fmamk_f32 v170, v170, 0x3a800000, v167
	v_sqrt_f32_e32 v173, v121
	v_fmamk_f32 v171, v171, 0x3a800000, v167
	v_fmamk_f32 v172, v172, 0x3a800000, v167
	v_mul_f32_e32 v174, 0x4f800000, v170
	v_cmp_gt_f32_e64 s[6:7], s25, v170
	v_mul_f32_e32 v175, 0x4f800000, v171
	v_cmp_gt_f32_e64 s[0:1], s25, v171
	v_mul_f32_e32 v176, 0x4f800000, v172
	v_cmp_gt_f32_e64 s[4:5], s25, v172
	v_cndmask_b32_e64 v170, v170, v174, s[6:7]
	v_cndmask_b32_e64 v171, v171, v175, s[0:1]
	v_cndmask_b32_e64 v172, v172, v176, s[4:5]
	v_sqrt_f32_e32 v174, v170
	v_sqrt_f32_e32 v175, v171
	v_sqrt_f32_e32 v176, v172
	v_add_u32_e32 v177, -1, v173
	v_add_u32_e32 v178, 1, v173
	v_fma_f32 v179, -v177, v173, v121
	v_fma_f32 v180, -v178, v173, v121
	v_cmp_ge_f32_e64 s[8:9], 0, v179
	v_add_u32_e32 v179, 1, v174
	v_add_u32_e32 v181, -1, v175
	v_cndmask_b32_e64 v173, v173, v177, s[8:9]
	v_add_u32_e32 v177, -1, v174
	v_cmp_lt_f32_e64 s[8:9], 0, v180
	v_add_u32_e32 v183, -1, v176
	v_add_u32_e32 v182, 1, v175
	v_cndmask_b32_e64 v173, v173, v178, s[8:9]
	v_fma_f32 v178, -v177, v174, v170
	v_add_u32_e32 v184, 1, v176
	v_fma_f32 v180, -v179, v174, v170
	v_fma_f32 v185, -v181, v175, v171
	v_fma_f32 v187, -v183, v176, v172
	v_cmp_ge_f32_e64 s[8:9], 0, v178
	v_fma_f32 v186, -v182, v175, v171
	v_fma_f32 v188, -v184, v176, v172
	v_cndmask_b32_e64 v174, v174, v177, s[8:9]
	v_cmp_lt_f32_e64 s[8:9], 0, v180
	v_cmp_ge_f32_e64 s[10:11], 0, v185
	v_cmp_ge_f32_e64 s[12:13], 0, v187
	v_mul_f32_e32 v177, 0x37800000, v173
	v_cndmask_b32_e64 v175, v175, v181, s[10:11]
	v_cmp_lt_f32_e64 s[10:11], 0, v186
	v_cndmask_b32_e64 v176, v176, v183, s[12:13]
	v_cmp_lt_f32_e64 s[12:13], 0, v188
	v_cndmask_b32_e32 v173, v173, v177, vcc
	v_cndmask_b32_e64 v174, v174, v179, s[8:9]
	v_cmp_class_f32_e32 vcc, v121, v168
	v_cndmask_b32_e64 v175, v175, v182, s[10:11]
	v_cndmask_b32_e64 v176, v176, v184, s[12:13]
	v_cndmask_b32_e32 v121, v173, v121, vcc
	v_mul_f32_e32 v173, 0x37800000, v174
	v_mul_f32_e32 v177, 0x37800000, v175
	v_mul_f32_e32 v178, 0x37800000, v176
	v_div_scale_f32 v179, s[8:9], v121, v121, 1.0
	v_cndmask_b32_e64 v173, v174, v173, s[6:7]
	v_cmp_class_f32_e64 s[6:7], v170, v168
	v_cndmask_b32_e64 v174, v175, v177, s[0:1]
	v_cmp_class_f32_e64 s[0:1], v171, v168
	v_cndmask_b32_e64 v175, v176, v178, s[4:5]
	v_rcp_f32_e32 v176, v179
	v_cndmask_b32_e64 v173, v173, v170, s[6:7]
	v_cmp_class_f32_e64 s[4:5], v172, v168
	v_cndmask_b32_e64 v171, v174, v171, s[0:1]
	v_div_scale_f32 v174, s[0:1], v173, v173, 1.0
	v_cndmask_b32_e64 v172, v175, v172, s[4:5]
	v_div_scale_f32 v177, s[4:5], v171, v171, 1.0
	v_rcp_f32_e32 v183, v174
	v_div_scale_f32 v181, s[6:7], v172, v172, 1.0
	v_rcp_f32_e32 v184, v177
	v_rcp_f32_e32 v185, v181
	v_fma_f32 v170, -v179, v176, 1.0
	v_div_scale_f32 v180, vcc, 1.0, v121, 1.0
	v_fmac_f32_e32 v176, v170, v176
	v_mul_f32_e32 v170, v180, v176
	v_fma_f32 v186, -v174, v183, 1.0
	v_div_scale_f32 v175, s[0:1], 1.0, v173, 1.0
	v_fma_f32 v187, -v177, v184, 1.0
	v_fma_f32 v189, -v179, v170, v180
	v_fmac_f32_e32 v183, v186, v183
	v_div_scale_f32 v178, s[4:5], 1.0, v171, 1.0
	v_fma_f32 v188, -v181, v185, 1.0
	v_fmac_f32_e32 v184, v187, v184
	v_fmac_f32_e32 v170, v189, v176
	v_mul_f32_e32 v186, v175, v183
	v_div_scale_f32 v182, s[6:7], 1.0, v172, 1.0
	v_fmac_f32_e32 v185, v188, v185
	v_mul_f32_e32 v187, v178, v184
	v_fma_f32 v179, -v179, v170, v180
	v_fma_f32 v180, -v174, v186, v175
	v_mul_f32_e32 v188, v182, v185
	v_fma_f32 v189, -v177, v187, v178
	v_div_fmas_f32 v170, v179, v176, v170
	v_fmac_f32_e32 v186, v180, v183
	v_fma_f32 v190, -v181, v188, v182
	v_fmac_f32_e32 v187, v189, v184
	v_div_fixup_f32 v170, v170, v121, 1.0
	v_fma_f32 v121, -v174, v186, v175
	s_mov_b64 vcc, s[0:1]
	v_fmac_f32_e32 v188, v190, v185
	v_fma_f32 v174, -v177, v187, v178
	v_pk_mul_f32 v[46:47], v[46:47], v[170:171] op_sel_hi:[1,0]
	v_pk_mul_f32 v[44:45], v[44:45], v[170:171] op_sel_hi:[1,0]
	v_pk_mul_f32 v[42:43], v[42:43], v[170:171] op_sel_hi:[1,0]
	v_pk_mul_f32 v[40:41], v[40:41], v[170:171] op_sel_hi:[1,0]
	v_pk_mul_f32 v[38:39], v[38:39], v[170:171] op_sel_hi:[1,0]
	v_pk_mul_f32 v[36:37], v[36:37], v[170:171] op_sel_hi:[1,0]
	v_pk_mul_f32 v[34:35], v[34:35], v[170:171] op_sel_hi:[1,0]
	v_pk_mul_f32 v[32:33], v[32:33], v[170:171] op_sel_hi:[1,0]
	v_div_fmas_f32 v121, v121, v183, v186
	s_mov_b64 vcc, s[4:5]
	v_pk_add_f32 v[142:143], v[142:143], 1.0 op_sel_hi:[1,0]
	v_pk_add_f32 v[70:71], v[70:71], 1.0 op_sel_hi:[1,0]
	v_pk_add_f32 v[68:69], v[68:69], 1.0 op_sel_hi:[1,0]
	v_pk_add_f32 v[146:147], v[146:147], 1.0 op_sel_hi:[1,0]
	v_fma_f32 v175, -v181, v188, v182
	v_div_fixup_f32 v170, v121, v173, 1.0
	v_div_fmas_f32 v121, v174, v184, v187
	v_pk_mul_f32 v[32:33], v[0:1], v[32:33]
	v_pk_mul_f32 v[34:35], v[2:3], v[34:35]
	v_pk_mul_f32 v[36:37], v[12:13], v[36:37]
	v_pk_mul_f32 v[38:39], v[14:15], v[38:39]
	v_pk_mul_f32 v[40:41], v[4:5], v[40:41]
	v_pk_mul_f32 v[42:43], v[6:7], v[42:43]
	v_pk_mul_f32 v[44:45], v[8:9], v[44:45]
	v_pk_mul_f32 v[46:47], v[10:11], v[46:47]
	s_mov_b64 vcc, s[6:7]
	v_pk_mul_f32 v[98:99], v[98:99], v[170:171] op_sel_hi:[1,0]
	v_pk_mul_f32 v[96:97], v[96:97], v[170:171] op_sel_hi:[1,0]
	v_pk_mul_f32 v[94:95], v[94:95], v[170:171] op_sel_hi:[1,0]
	v_pk_mul_f32 v[92:93], v[92:93], v[170:171] op_sel_hi:[1,0]
	v_pk_mul_f32 v[90:91], v[90:91], v[170:171] op_sel_hi:[1,0]
	v_pk_mul_f32 v[88:89], v[88:89], v[170:171] op_sel_hi:[1,0]
	v_pk_mul_f32 v[86:87], v[86:87], v[170:171] op_sel_hi:[1,0]
	v_pk_mul_f32 v[84:85], v[84:85], v[170:171] op_sel_hi:[1,0]
	v_div_fixup_f32 v170, v121, v171, 1.0
	v_div_fmas_f32 v121, v175, v185, v188
	v_pk_fma_f32 v[46:47], v[148:149], v[46:47], v[30:31]
; #define GAS __attribute__((address_space(1)))
; __device__ __forceinline__ unsigned f2bf(float f) { unsigned u = __builtin_bit_cast(unsigned, f); return (u + 0x7fffu + ((u >> 16) & 1u)) >> 16; }
; __device__ __forceinline__ unsigned pk2(float lo, float hi) { return f2bf(lo) | (f2bf(hi) << 16); }
; __device__ __forceinline__ void normmod_row(const float* xrow, const float* nw, const float* sh, const float* sc, int lane, f32x4 (&v)[4]) {
;     ...
;     for (int j = 0; j < 4; ++j) { const f32x4 w = ((const GAS f32x4*)nw)[lane + 64 * j]; v[j] = v[j] * rstd * w;
;         if (sc) { const f32x4 a = ((const GAS f32x4*)sc)[lane + 64 * j], b = ((const GAS f32x4*)sh)[lane + 64 * j]; v[j] = v[j] * (1.f + a) + b; } }
	v_pk_fma_f32 v[44:45], v[150:151], v[44:45], v[28:29]
	v_pk_fma_f32 v[42:43], v[144:145], v[42:43], v[26:27]
	v_pk_fma_f32 v[40:41], v[146:147], v[40:41], v[24:25]
	v_pk_fma_f32 v[38:39], v[70:71], v[38:39], v[22:23]
	v_pk_fma_f32 v[36:37], v[68:69], v[36:37], v[20:21]
	v_pk_fma_f32 v[34:35], v[140:141], v[34:35], v[18:19]
	v_pk_fma_f32 v[32:33], v[142:143], v[32:33], v[16:17]
	v_pk_mul_f32 v[82:83], v[82:83], v[170:171] op_sel_hi:[1,0]
	v_pk_mul_f32 v[80:81], v[80:81], v[170:171] op_sel_hi:[1,0]
	v_pk_mul_f32 v[78:79], v[78:79], v[170:171] op_sel_hi:[1,0]
	v_pk_mul_f32 v[76:77], v[76:77], v[170:171] op_sel_hi:[1,0]
	v_pk_mul_f32 v[74:75], v[74:75], v[170:171] op_sel_hi:[1,0]
	v_pk_mul_f32 v[72:73], v[72:73], v[170:171] op_sel_hi:[1,0]
	v_pk_mul_f32 v[66:67], v[66:67], v[170:171] op_sel_hi:[1,0]
	v_pk_mul_f32 v[64:65], v[64:65], v[170:171] op_sel_hi:[1,0]
	v_div_fixup_f32 v170, v121, v172, 1.0
	v_pk_mul_f32 v[84:85], v[0:1], v[84:85]
	v_pk_mul_f32 v[86:87], v[2:3], v[86:87]
	v_pk_mul_f32 v[88:89], v[12:13], v[88:89]
	v_pk_mul_f32 v[90:91], v[14:15], v[90:91]
	v_bfe_u32 v121, v32, 16, 1
	v_bfe_u32 v171, v33, 16, 1
	v_bfe_u32 v172, v34, 16, 1
	v_bfe_u32 v173, v35, 16, 1
	v_bfe_u32 v174, v36, 16, 1
	v_bfe_u32 v175, v37, 16, 1
	v_bfe_u32 v176, v38, 16, 1
	v_bfe_u32 v177, v39, 16, 1
	v_bfe_u32 v178, v40, 16, 1
	v_bfe_u32 v179, v41, 16, 1
	v_bfe_u32 v180, v42, 16, 1
	v_bfe_u32 v181, v43, 16, 1
	v_bfe_u32 v182, v44, 16, 1
	v_bfe_u32 v183, v45, 16, 1
	v_bfe_u32 v184, v46, 16, 1
	v_bfe_u32 v185, v47, 16, 1
	v_pk_mul_f32 v[94:95], v[6:7], v[94:95]
	v_pk_mul_f32 v[96:97], v[8:9], v[96:97]
	v_pk_mul_f32 v[98:99], v[10:11], v[98:99]
	v_pk_mul_f32 v[92:93], v[4:5], v[92:93]
	v_pk_mul_f32 v[62:63], v[62:63], v[170:171] op_sel_hi:[1,0]
	v_pk_mul_f32 v[60:61], v[60:61], v[170:171] op_sel_hi:[1,0]
	v_pk_mul_f32 v[58:59], v[58:59], v[170:171] op_sel_hi:[1,0]
	v_pk_mul_f32 v[56:57], v[56:57], v[170:171] op_sel_hi:[1,0]
	v_pk_mul_f32 v[54:55], v[54:55], v[170:171] op_sel_hi:[1,0]
	v_pk_mul_f32 v[52:53], v[52:53], v[170:171] op_sel_hi:[1,0]
	v_pk_mul_f32 v[50:51], v[50:51], v[170:171] op_sel_hi:[1,0]
	v_pk_mul_f32 v[48:49], v[48:49], v[170:171] op_sel_hi:[1,0]
	v_pk_mul_f32 v[64:65], v[0:1], v[64:65]
	v_pk_mul_f32 v[66:67], v[2:3], v[66:67]
	v_pk_mul_f32 v[72:73], v[12:13], v[72:73]
	v_pk_mul_f32 v[74:75], v[14:15], v[74:75]
	v_add3_u32 v121, v32, v121, s27
	v_add3_u32 v170, v33, v171, s27
	v_add3_u32 v171, v34, v172, s27
	v_add3_u32 v172, v35, v173, s27
	v_add3_u32 v173, v36, v174, s27
	v_add3_u32 v174, v37, v175, s27
	v_add3_u32 v175, v38, v176, s27
	v_add3_u32 v176, v39, v177, s27
	v_add3_u32 v177, v40, v178, s27
	v_add3_u32 v178, v41, v179, s27
	v_add3_u32 v179, v42, v180, s27
	v_add3_u32 v180, v43, v181, s27
	v_add3_u32 v181, v44, v182, s27
	v_add3_u32 v182, v45, v183, s27
	v_add3_u32 v183, v46, v184, s27
	v_add3_u32 v184, v47, v185, s27
	v_pk_fma_f32 v[32:33], v[148:149], v[98:99], v[30:31]
	v_pk_fma_f32 v[34:35], v[150:151], v[96:97], v[28:29]
	v_pk_fma_f32 v[36:37], v[144:145], v[94:95], v[26:27]
	v_pk_fma_f32 v[40:41], v[70:71], v[90:91], v[22:23]
	v_pk_fma_f32 v[42:43], v[68:69], v[88:89], v[20:21]
	v_pk_fma_f32 v[44:45], v[140:141], v[86:87], v[18:19]
	v_pk_fma_f32 v[46:47], v[142:143], v[84:85], v[16:17]
	v_pk_mul_f32 v[76:77], v[4:5], v[76:77]
	v_pk_mul_f32 v[78:79], v[6:7], v[78:79]
	v_pk_mul_f32 v[80:81], v[8:9], v[80:81]
	v_pk_mul_f32 v[82:83], v[10:11], v[82:83]
	v_pk_fma_f32 v[38:39], v[146:147], v[92:93], v[24:25]
	v_pk_mul_f32 v[0:1], v[0:1], v[48:49]
	v_pk_mul_f32 v[2:3], v[2:3], v[50:51]
	v_pk_mul_f32 v[12:13], v[12:13], v[52:53]
	v_pk_mul_f32 v[14:15], v[14:15], v[54:55]
	v_lshrrev_b32_e32 v84, 16, v121
	v_lshrrev_b32_e32 v86, 16, v173
	v_lshrrev_b32_e32 v88, 16, v177
	v_lshrrev_b32_e32 v90, 16, v181
	v_bfe_u32 v92, v46, 16, 1
	v_pk_mul_f32 v[4:5], v[4:5], v[56:57]
	v_pk_mul_f32 v[6:7], v[6:7], v[58:59]
	v_bfe_u32 v94, v44, 16, 1
	v_bfe_u32 v96, v42, 16, 1
	v_pk_mul_f32 v[8:9], v[8:9], v[60:61]
	v_pk_mul_f32 v[10:11], v[10:11], v[62:63]
	v_bfe_u32 v98, v40, 16, 1
	v_bfe_u32 v173, v36, 16, 1
	v_bfe_u32 v177, v34, 16, 1
	v_bfe_u32 v181, v32, 16, 1
	v_pk_fma_f32 v[48:49], v[148:149], v[82:83], v[30:31]
	v_pk_fma_f32 v[50:51], v[150:151], v[80:81], v[28:29]
	v_pk_fma_f32 v[52:53], v[144:145], v[78:79], v[26:27]
	v_pk_fma_f32 v[54:55], v[146:147], v[76:77], v[24:25]
	v_pk_fma_f32 v[56:57], v[70:71], v[74:75], v[22:23]
	v_pk_fma_f32 v[58:59], v[68:69], v[72:73], v[20:21]
	v_pk_fma_f32 v[60:61], v[140:141], v[66:67], v[18:19]
	v_pk_fma_f32 v[62:63], v[142:143], v[64:65], v[16:17]
	v_lshrrev_b32_e32 v85, 16, v171
	v_lshrrev_b32_e32 v87, 16, v175
	v_lshrrev_b32_e32 v89, 16, v179
	v_lshrrev_b32_e32 v91, 16, v183
	v_bfe_u32 v93, v47, 16, 1
	v_bfe_u32 v95, v45, 16, 1
	v_bfe_u32 v97, v43, 16, 1
	v_bfe_u32 v99, v41, 16, 1
	v_bfe_u32 v121, v38, 16, 1
	v_bfe_u32 v175, v37, 16, 1
	v_bfe_u32 v179, v35, 16, 1
	v_and_or_b32 v64, v170, s28, v84
	v_and_or_b32 v66, v174, s28, v86
	v_and_or_b32 v72, v178, s28, v88
	v_and_or_b32 v74, v182, s28, v90
	v_add3_u32 v46, v46, v92, s27
	v_add3_u32 v44, v44, v94, s27
	v_add3_u32 v42, v42, v96, s27
	v_add3_u32 v40, v40, v98, s27
	v_add3_u32 v36, v36, v173, s27
	v_add3_u32 v34, v34, v177, s27
	v_add3_u32 v32, v32, v181, s27
	v_bfe_u32 v76, v62, 16, 1
	v_bfe_u32 v78, v60, 16, 1
	v_bfe_u32 v80, v58, 16, 1
	v_bfe_u32 v82, v56, 16, 1
	v_bfe_u32 v84, v54, 16, 1
	v_bfe_u32 v86, v52, 16, 1
	v_bfe_u32 v88, v50, 16, 1
	v_bfe_u32 v90, v48, 16, 1
; #define LAS __attribute__((address_space(3)))
; #define GAS __attribute__((address_space(1)))
; __device__ __forceinline__ unsigned pk2(float lo, float hi) { return f2bf(lo) | (f2bf(hi) << 16); }
; #define LDS_WAIT() asm volatile("s_waitcnt lgkmcnt(0)" ::: "memory")
; __device__ __forceinline__ void phase_upass(Frame& F) {
;     ...
;         for (int t = 0; t < 4; ++t) { f32x4 v[4]; normmod_row(x + (size_t)(m0 + t) * D, nw, mb, mb + D, F.lane, v);
; #pragma unroll
;             for (int j = 0; j < 4; ++j) { u32x2 o; o.x = pk2(v[j].x, v[j].y); o.y = pk2(v[j].z, v[j].w); *(LAS u32x2*)(tl + t * 1024 + 4 * F.lane + 256 * j) = o; } }
;         LDS_WAIT(); asm volatile("" ::: "memory");
; #pragma unroll
;         for (int i = 0; i < 8; ++i) { const int g = 8 * i + (F.lane >> 3), pc = F.lane & 7, t = pc >> 1, hf = pc & 1;
;             const u32x4 o = *(const LAS u32x4*)(tl + t * 1024 + g * 16 + hf * 8);
;             *(GAS u32x4*)(UAUG + ((size_t)g * BC + b * NCH + c) * UA + (s0 + t) * 16 + hf * 8) = o; }
;         LDS_WAIT(); asm volatile("" ::: "memory");
	v_pk_fma_f32 v[14:15], v[70:71], v[14:15], v[22:23]
	v_pk_fma_f32 v[12:13], v[68:69], v[12:13], v[20:21]
	v_pk_fma_f32 v[2:3], v[140:141], v[2:3], v[18:19]
	v_pk_fma_f32 v[0:1], v[142:143], v[0:1], v[16:17]
	v_bfe_u32 v171, v39, 16, 1
	v_bfe_u32 v183, v33, 16, 1
	v_and_or_b32 v65, v172, s28, v85
	v_and_or_b32 v67, v176, s28, v87
	v_and_or_b32 v73, v180, s28, v89
	v_and_or_b32 v75, v184, s28, v91
	v_add3_u32 v47, v47, v93, s27
	v_add3_u32 v45, v45, v95, s27
	v_add3_u32 v43, v43, v97, s27
	v_add3_u32 v41, v41, v99, s27
	v_add3_u32 v38, v38, v121, s27
	v_add3_u32 v37, v37, v175, s27
	v_add3_u32 v35, v35, v179, s27
	v_bfe_u32 v77, v63, 16, 1
	v_bfe_u32 v79, v61, 16, 1
	v_bfe_u32 v81, v59, 16, 1
	v_bfe_u32 v83, v57, 16, 1
	v_bfe_u32 v85, v55, 16, 1
	v_bfe_u32 v87, v53, 16, 1
	v_bfe_u32 v89, v51, 16, 1
	v_bfe_u32 v91, v49, 16, 1
	v_pk_fma_f32 v[10:11], v[148:149], v[10:11], v[30:31]
	v_pk_fma_f32 v[8:9], v[150:151], v[8:9], v[28:29]
	v_pk_fma_f32 v[6:7], v[144:145], v[6:7], v[26:27]
	v_pk_fma_f32 v[4:5], v[146:147], v[4:5], v[24:25]
	v_lshrrev_b32_e32 v16, 16, v46
	v_lshrrev_b32_e32 v17, 16, v44
	v_lshrrev_b32_e32 v18, 16, v42
	v_lshrrev_b32_e32 v19, 16, v40
	v_lshrrev_b32_e32 v21, 16, v36
	v_lshrrev_b32_e32 v22, 16, v34
	v_lshrrev_b32_e32 v23, 16, v32
	v_add3_u32 v24, v62, v76, s27
	v_add3_u32 v26, v60, v78, s27
	v_add3_u32 v28, v58, v80, s27
	v_add3_u32 v30, v56, v82, s27
	v_add3_u32 v32, v54, v84, s27
	v_add3_u32 v36, v52, v86, s27
	v_add3_u32 v40, v50, v88, s27
	v_add3_u32 v44, v48, v90, s27
	v_bfe_u32 v48, v0, 16, 1
	v_bfe_u32 v50, v2, 16, 1
	v_bfe_u32 v52, v12, 16, 1
	v_bfe_u32 v54, v14, 16, 1
	v_add3_u32 v39, v39, v171, s27
	v_add3_u32 v33, v33, v183, s27
	v_lshrrev_b32_e32 v20, 16, v38
	v_add3_u32 v25, v63, v77, s27
	v_add3_u32 v27, v61, v79, s27
	v_add3_u32 v29, v59, v81, s27
	v_add3_u32 v31, v57, v83, s27
	v_add3_u32 v34, v55, v85, s27
	v_add3_u32 v38, v53, v87, s27
	v_add3_u32 v42, v51, v89, s27
	v_add3_u32 v46, v49, v91, s27
	v_bfe_u32 v49, v1, 16, 1
	v_bfe_u32 v51, v3, 16, 1
	v_bfe_u32 v53, v13, 16, 1
	v_bfe_u32 v55, v15, 16, 1
	v_bfe_u32 v56, v4, 16, 1
	v_bfe_u32 v58, v6, 16, 1
	v_bfe_u32 v60, v8, 16, 1
	v_bfe_u32 v62, v10, 16, 1
	v_and_or_b32 v16, v47, s28, v16
	v_and_or_b32 v17, v45, s28, v17
	v_and_or_b32 v18, v43, s28, v18
	v_and_or_b32 v19, v41, s28, v19
	v_and_or_b32 v21, v37, s28, v21
	v_and_or_b32 v22, v35, s28, v22
	v_lshrrev_b32_e32 v24, 16, v24
	v_lshrrev_b32_e32 v26, 16, v26
	v_lshrrev_b32_e32 v28, 16, v28
	v_lshrrev_b32_e32 v30, 16, v30
	v_lshrrev_b32_e32 v35, 16, v40
	v_add3_u32 v37, v0, v48, s27
	v_add3_u32 v40, v2, v50, s27
	v_add3_u32 v12, v12, v52, s27
	v_add3_u32 v14, v14, v54, s27
	ds_write2st64_b64 v169, v[64:65], v[66:67] offset1:1
	ds_write2st64_b64 v169, v[72:73], v[74:75] offset0:2 offset1:3
	v_bfe_u32 v57, v5, 16, 1
	v_bfe_u32 v59, v7, 16, 1
	v_bfe_u32 v61, v9, 16, 1
	v_bfe_u32 v63, v11, 16, 1
	v_and_or_b32 v20, v39, s28, v20
	v_and_or_b32 v23, v33, s28, v23
	v_lshrrev_b32_e32 v32, 16, v32
	v_lshrrev_b32_e32 v33, 16, v36
	v_lshrrev_b32_e32 v36, 16, v44
	v_add3_u32 v39, v1, v49, s27
	v_add3_u32 v41, v3, v51, s27
	v_add3_u32 v13, v13, v53, s27
	v_add3_u32 v15, v15, v55, s27
	v_add3_u32 v43, v4, v56, s27
	v_add3_u32 v45, v6, v58, s27
	v_add3_u32 v8, v8, v60, s27
	v_add3_u32 v10, v10, v62, s27
	ds_write2st64_b64 v169, v[16:17], v[18:19] offset0:4 offset1:5
	ds_write2st64_b64 v169, v[20:21], v[22:23] offset0:6 offset1:7
	v_and_or_b32 v0, v25, s28, v24
	v_and_or_b32 v1, v27, s28, v26
	v_and_or_b32 v2, v29, s28, v28
	v_and_or_b32 v3, v31, s28, v30
	v_lshrrev_b32_e32 v16, 16, v37
	v_lshrrev_b32_e32 v17, 16, v40
	v_lshrrev_b32_e32 v12, 16, v12
	v_lshrrev_b32_e32 v14, 16, v14
	v_add3_u32 v44, v5, v57, s27
	v_add3_u32 v47, v7, v59, s27
	v_add3_u32 v9, v9, v61, s27
	v_add3_u32 v11, v11, v63, s27
	v_and_or_b32 v4, v34, s28, v32
	v_and_or_b32 v5, v38, s28, v33
	v_and_or_b32 v6, v42, s28, v35
	v_and_or_b32 v7, v46, s28, v36
	v_lshrrev_b32_e32 v18, 16, v43
	v_lshrrev_b32_e32 v19, 16, v45
	v_lshrrev_b32_e32 v8, 16, v8
	v_lshrrev_b32_e32 v10, 16, v10
	ds_write2st64_b64 v169, v[0:1], v[2:3] offset0:8 offset1:9
	ds_write2st64_b64 v169, v[4:5], v[6:7] offset0:10 offset1:11
	v_and_or_b32 v0, v39, s28, v16
	v_and_or_b32 v1, v41, s28, v17
	v_and_or_b32 v2, v13, s28, v12
	v_and_or_b32 v3, v15, s28, v14
	v_and_or_b32 v4, v44, s28, v18
	v_and_or_b32 v5, v47, s28, v19
	v_and_or_b32 v6, v9, s28, v8
	v_and_or_b32 v7, v11, s28, v10
	ds_write2st64_b64 v169, v[0:1], v[2:3] offset0:12 offset1:13
	ds_write2st64_b64 v169, v[4:5], v[6:7] offset0:14 offset1:15
	s_waitcnt lgkmcnt(0)
	ds_read_b128 v[0:3], v159
	ds_read_b128 v[4:7], v160
	ds_read_b128 v[8:11], v161
	ds_read_b128 v[12:15], v162
	ds_read_b128 v[16:19], v163
	ds_read_b128 v[20:23], v164
	ds_read_b128 v[24:27], v165
	ds_read_b128 v[28:31], v166
	s_waitcnt lgkmcnt(7)
	global_store_dwordx4 v[124:125], v[0:3], off
	s_waitcnt lgkmcnt(6)
	global_store_dwordx4 v[126:127], v[4:7], off
	s_waitcnt lgkmcnt(5)
	global_store_dwordx4 v[128:129], v[8:11], off
	s_waitcnt lgkmcnt(4)
	global_store_dwordx4 v[130:131], v[12:15], off
	s_waitcnt lgkmcnt(3)
	global_store_dwordx4 v[132:133], v[16:19], off
	s_waitcnt lgkmcnt(2)
	global_store_dwordx4 v[134:135], v[20:23], off
	s_waitcnt lgkmcnt(1)
	global_store_dwordx4 v[136:137], v[24:27], off
	s_waitcnt lgkmcnt(0)
	global_store_dwordx4 v[138:139], v[28:31], off
	s_waitcnt lgkmcnt(0)
	s_add_i32 s20, s20, s24
	s_cmpk_gt_i32 s17, 0xfff
	s_cbranch_scc0 .LBB0_278

; __device__ __forceinline__ int lane_id() { return (int)__builtin_amdgcn_mbcnt_hi(~0u, __builtin_amdgcn_mbcnt_lo(~0u, 0u)); }
; __device__ __forceinline__ unsigned xb_ld(unsigned* p)              { return __hip_atomic_load(p, __ATOMIC_RELAXED, __HIP_MEMORY_SCOPE_AGENT); }
; __device__ __forceinline__ unsigned xb_add(unsigned* p, unsigned v) { return __hip_atomic_fetch_add(p, v, __ATOMIC_RELAXED, __HIP_MEMORY_SCOPE_AGENT); }
;     ...
;     if (b.wave == 0) {
;         unsigned* bar = b.bar; const int l_ = lane_id(); unsigned gen_ = 0u;
;         if (l_ == 0) {
;             __builtin_amdgcn_s_waitcnt(0);
;             unsigned nloc = b.st[0], nx = b.st[1];
;             if (nloc == 0u) { xcd_barrier_complete(bar, b.x, nloc, nx); b.st[0] = nloc; b.st[1] = nx; }
;             const unsigned old = xb_add(&bar[XB_XSUB(b.x)], 1u);
;             gen_ = old / nloc;
;             if (old + 1u == (gen_ + 1u) * nloc) {
;                 if (!wt_only) __builtin_amdgcn_fence(__ATOMIC_RELEASE, "agent");
;                 asm volatile("s_waitcnt vmcnt(0)" ::: "memory");
;                 __hip_atomic_store(&bar[XB_XGEN(b.x)], gen_ + 1u, __ATOMIC_RELAXED, __HIP_MEMORY_SCOPE_AGENT);
;             }
;         }
;         gen_ = __builtin_amdgcn_readfirstlane(gen_);
;         const bool act_ = (l_ < 16) && (xb_ld(&bar[XB_XCNT(l_ & 15)]) > 0u);
.LBB0_371:
	v_cndmask_b32_e64 v0, 0, 1, s[8:9]
	v_cmp_ne_u32_e64 s[0:1], 1, v0
	s_andn2_b64 vcc, exec, s[8:9]
	s_nop 0
	v_writelane_b32 v252, s0, 36
	s_nop 1
	v_writelane_b32 v252, s1, 37
	s_cbranch_vccnz .LBB0_409
	v_mbcnt_lo_u32_b32 v0, -1, 0
	v_mbcnt_hi_u32_b32 v0, -1, v0
	v_and_b32_e32 v31, 15, v0
	v_lshlrev_b32_e32 v31, 8, v31
	global_load_dword v30, v31, s[94:95] offset:1024 sc1
	v_mov_b32_e32 v2, 0
	v_cmp_ne_u32_e64 s[4:5], 0, v0
	v_cmp_eq_u32_e32 vcc, 0, v0
	s_and_saveexec_b64 s[6:7], vcc
	s_cbranch_execz .LBB0_393
	s_add_i32 s0, 0, 0x23f60
	v_mov_b32_e32 v1, s0
	s_waitcnt vmcnt(1) expcnt(0) lgkmcnt(0)
	ds_read_b32 v1, v1
	s_add_i32 s0, 0, 0x23f64
	v_mov_b32_e32 v2, s0
	ds_read_b32 v2, v2
	s_waitcnt lgkmcnt(1)
	v_cmp_ne_u32_e32 vcc, 0, v1
	s_cbranch_vccnz .LBB0_388
	v_readlane_b32 s8, v252, 0
	v_readlane_b32 s9, v252, 1
	s_load_dwordx2 s[0:1], s[8:9], 0x4
	s_add_u32 s8, s34, 0x4200
	s_addc_u32 s9, s35, 0
	s_add_u32 s10, s34, 0x4400
	s_addc_u32 s11, s35, 0
	s_add_u32 s12, s34, 0x4500
	s_addc_u32 s13, s35, 0
	s_add_u32 s14, s34, 0x4600
	s_addc_u32 s15, s35, 0
	s_add_u32 s20, s34, 0x4700
	s_addc_u32 s21, s35, 0
	s_add_u32 s22, s34, 0x4800
	s_addc_u32 s23, s35, 0
	s_add_u32 s30, s34, 0x4900
	s_addc_u32 s31, s35, 0
	s_add_u32 s44, s34, 0x4a00
	s_addc_u32 s45, s35, 0
	s_add_u32 s46, s34, 0x4b00
	s_addc_u32 s47, s35, 0
	s_add_u32 s52, s34, 0x4c00
	s_addc_u32 s53, s35, 0
	s_add_u32 s54, s34, 0x4d00
	s_addc_u32 s55, s35, 0
	s_add_u32 s56, s34, 0x4e00
	s_addc_u32 s57, s35, 0
	s_add_u32 s58, s34, 0x4f00
	s_addc_u32 s59, s35, 0
	s_add_u32 s60, s34, 0x5000
	s_addc_u32 s61, s35, 0
	s_add_u32 s62, s34, 0x5100
	s_addc_u32 s63, s35, 0
	s_add_u32 s64, s34, 0x5200
	s_addc_u32 s65, s35, 0
	s_waitcnt lgkmcnt(0)
	s_mul_i32 s0, s0, s33
	s_add_u32 s66, s34, 0x5300
	s_mul_i32 s0, s0, s1
	s_addc_u32 s67, s35, 0
	s_mov_b32 s1, 1
	v_mov_b32_e32 v17, 0
	s_branch .LBB0_376

; __device__ __forceinline__ unsigned xb_ld(unsigned* p)              { return __hip_atomic_load(p, __ATOMIC_RELAXED, __HIP_MEMORY_SCOPE_AGENT); }
;     ...
;         gen_ = __builtin_amdgcn_readfirstlane(gen_);
;         const bool act_ = (l_ < 16) && (xb_ld(&bar[XB_XCNT(l_ & 15)]) > 0u);
.LBB0_393:
	s_or_b64 exec, exec, s[6:7]
	v_cmp_gt_i32_e32 vcc, 16, v0
	v_lshlrev_b32_e32 v0, 6, v0
	v_and_b32_e32 v0, 0x3c0, v0
	v_readfirstlane_b32 s0, v2
	v_mov_b32_e32 v1, 0
	s_mov_b64 s[6:7], 0
	v_lshlrev_b32_e32 v0, 2, v0
	s_mov_b64 s[8:9], 0
	s_and_saveexec_b64 s[10:11], vcc
	s_cbranch_execz .LBB0_395
	s_waitcnt vmcnt(0)
	v_mov_b32_e32 v2, v30
	v_cmp_ne_u32_e32 vcc, 0, v2
	s_and_b64 s[8:9], vcc, exec

; __device__ __forceinline__ int lane_id() { return (int)__builtin_amdgcn_mbcnt_hi(~0u, __builtin_amdgcn_mbcnt_lo(~0u, 0u)); }
; __device__ __forceinline__ unsigned xb_ld(unsigned* p)              { return __hip_atomic_load(p, __ATOMIC_RELAXED, __HIP_MEMORY_SCOPE_AGENT); }
; __device__ __forceinline__ unsigned xb_add(unsigned* p, unsigned v) { return __hip_atomic_fetch_add(p, v, __ATOMIC_RELAXED, __HIP_MEMORY_SCOPE_AGENT); }
;     ...
;     if (b.wave == 0) {
;         unsigned* bar = b.bar; const int l_ = lane_id(); unsigned gen_ = 0u;
;         if (l_ == 0) {
;             __builtin_amdgcn_s_waitcnt(0);
;             unsigned nloc = b.st[0], nx = b.st[1];
;             if (nloc == 0u) { xcd_barrier_complete(bar, b.x, nloc, nx); b.st[0] = nloc; b.st[1] = nx; }
;             const unsigned old = xb_add(&bar[XB_XSUB(b.x)], 1u);
;             gen_ = old / nloc;
;             if (old + 1u == (gen_ + 1u) * nloc) {
;                 if (!wt_only) __builtin_amdgcn_fence(__ATOMIC_RELEASE, "agent");
;                 asm volatile("s_waitcnt vmcnt(0)" ::: "memory");
;                 __hip_atomic_store(&bar[XB_XGEN(b.x)], gen_ + 1u, __ATOMIC_RELAXED, __HIP_MEMORY_SCOPE_AGENT);
;             }
;         }
;         gen_ = __builtin_amdgcn_readfirstlane(gen_);
;         const bool act_ = (l_ < 16) && (xb_ld(&bar[XB_XCNT(l_ & 15)]) > 0u);
.LBB0_496:
	v_readlane_b32 s4, v252, 36
	v_readlane_b32 s5, v252, 37
	s_and_b64 vcc, exec, s[4:5]
	s_cbranch_vccnz .LBB0_534
	v_mbcnt_lo_u32_b32 v0, -1, 0
	v_mbcnt_hi_u32_b32 v0, -1, v0
	v_and_b32_e32 v31, 15, v0
	v_lshlrev_b32_e32 v31, 8, v31
	global_load_dword v30, v31, s[94:95] offset:1024 sc1
	v_mov_b32_e32 v2, 0
	v_cmp_ne_u32_e64 s[6:7], 0, v0
	v_cmp_eq_u32_e32 vcc, 0, v0
	s_and_saveexec_b64 s[10:11], vcc
	s_cbranch_execz .LBB0_518
	s_add_i32 s4, 0, 0x23f60
	v_mov_b32_e32 v1, s4
	s_waitcnt vmcnt(1) expcnt(0) lgkmcnt(0)
	ds_read_b32 v1, v1
	s_add_i32 s4, 0, 0x23f64
	v_mov_b32_e32 v2, s4
	ds_read_b32 v2, v2
	s_waitcnt lgkmcnt(1)
	v_cmp_ne_u32_e32 vcc, 0, v1
	s_cbranch_vccnz .LBB0_513
	v_readlane_b32 s12, v252, 0
	v_readlane_b32 s13, v252, 1
	s_load_dwordx2 s[4:5], s[12:13], 0x4
	s_add_u32 s12, s34, 0x4200
	s_addc_u32 s13, s35, 0
	s_add_u32 s14, s34, 0x4400
	s_addc_u32 s15, s35, 0
	s_add_u32 s16, s34, 0x4500
	s_addc_u32 s17, s35, 0
	s_add_u32 s18, s34, 0x4600
	s_addc_u32 s19, s35, 0
	s_add_u32 s20, s34, 0x4700
	s_addc_u32 s21, s35, 0
	s_add_u32 s22, s34, 0x4800
	s_addc_u32 s23, s35, 0
	s_add_u32 s30, s34, 0x4900
	s_addc_u32 s31, s35, 0
	s_add_u32 s44, s34, 0x4a00
	s_addc_u32 s45, s35, 0
	s_add_u32 s46, s34, 0x4b00
	s_addc_u32 s47, s35, 0
	s_add_u32 s52, s34, 0x4c00
	s_addc_u32 s53, s35, 0
	s_add_u32 s54, s34, 0x4d00
	s_addc_u32 s55, s35, 0
	s_add_u32 s56, s34, 0x4e00
	s_addc_u32 s57, s35, 0
	s_add_u32 s58, s34, 0x4f00
	s_addc_u32 s59, s35, 0
	s_add_u32 s60, s34, 0x5000
	s_addc_u32 s61, s35, 0
	s_add_u32 s62, s34, 0x5100
	s_addc_u32 s63, s35, 0
	s_add_u32 s64, s34, 0x5200
	s_addc_u32 s65, s35, 0
	s_waitcnt lgkmcnt(0)
	s_mul_i32 s4, s4, s33
	s_add_u32 s66, s34, 0x5300
	s_mul_i32 s4, s4, s5
	s_addc_u32 s67, s35, 0
	s_mov_b32 s5, 1
	v_mov_b32_e32 v17, 0
	s_branch .LBB0_501

; __device__ __forceinline__ unsigned xb_ld(unsigned* p)              { return __hip_atomic_load(p, __ATOMIC_RELAXED, __HIP_MEMORY_SCOPE_AGENT); }
;     ...
;         gen_ = __builtin_amdgcn_readfirstlane(gen_);
;         const bool act_ = (l_ < 16) && (xb_ld(&bar[XB_XCNT(l_ & 15)]) > 0u);
.LBB0_518:
	s_or_b64 exec, exec, s[10:11]
	v_cmp_gt_i32_e32 vcc, 16, v0
	v_lshlrev_b32_e32 v0, 6, v0
	v_and_b32_e32 v0, 0x3c0, v0
	v_readfirstlane_b32 s4, v2
	v_mov_b32_e32 v1, 0
	s_mov_b64 s[10:11], 0
	v_lshlrev_b32_e32 v0, 2, v0
	s_mov_b64 s[12:13], 0
	s_and_saveexec_b64 s[14:15], vcc
	s_cbranch_execz .LBB0_520
	s_waitcnt vmcnt(0)
	v_mov_b32_e32 v2, v30
	v_cmp_ne_u32_e32 vcc, 0, v2
	s_and_b64 s[12:13], vcc, exec

; __device__ __forceinline__ int lane_id() { return (int)__builtin_amdgcn_mbcnt_hi(~0u, __builtin_amdgcn_mbcnt_lo(~0u, 0u)); }
; __device__ __forceinline__ unsigned xb_ld(unsigned* p)              { return __hip_atomic_load(p, __ATOMIC_RELAXED, __HIP_MEMORY_SCOPE_AGENT); }
; __device__ __forceinline__ unsigned xb_add(unsigned* p, unsigned v) { return __hip_atomic_fetch_add(p, v, __ATOMIC_RELAXED, __HIP_MEMORY_SCOPE_AGENT); }
;     ...
;     if (b.wave == 0) {
;         unsigned* bar = b.bar; const int l_ = lane_id(); unsigned gen_ = 0u;
;         if (l_ == 0) {
;             __builtin_amdgcn_s_waitcnt(0);
;             unsigned nloc = b.st[0], nx = b.st[1];
;             if (nloc == 0u) { xcd_barrier_complete(bar, b.x, nloc, nx); b.st[0] = nloc; b.st[1] = nx; }
;             const unsigned old = xb_add(&bar[XB_XSUB(b.x)], 1u);
;             gen_ = old / nloc;
;             if (old + 1u == (gen_ + 1u) * nloc) {
;                 if (!wt_only) __builtin_amdgcn_fence(__ATOMIC_RELEASE, "agent");
;                 asm volatile("s_waitcnt vmcnt(0)" ::: "memory");
;                 __hip_atomic_store(&bar[XB_XGEN(b.x)], gen_ + 1u, __ATOMIC_RELAXED, __HIP_MEMORY_SCOPE_AGENT);
;             }
;         }
;         gen_ = __builtin_amdgcn_readfirstlane(gen_);
;         const bool act_ = (l_ < 16) && (xb_ld(&bar[XB_XCNT(l_ & 15)]) > 0u);
.LBB0_578:
	v_readlane_b32 s0, v252, 36
	v_readlane_b32 s1, v252, 37
	s_and_b64 vcc, exec, s[0:1]
	s_cbranch_vccnz .LBB0_616
	v_mbcnt_lo_u32_b32 v0, -1, 0
	v_mbcnt_hi_u32_b32 v0, -1, v0
	v_and_b32_e32 v31, 15, v0
	v_lshlrev_b32_e32 v31, 8, v31
	global_load_dword v30, v31, s[94:95] offset:1024 sc1
	v_mov_b32_e32 v2, 0
	v_cmp_ne_u32_e64 s[8:9], 0, v0
	v_cmp_eq_u32_e32 vcc, 0, v0
	s_and_saveexec_b64 s[10:11], vcc
	s_cbranch_execz .LBB0_600
	s_add_i32 s0, 0, 0x23f60
	v_mov_b32_e32 v1, s0
	s_waitcnt vmcnt(1) expcnt(0) lgkmcnt(0)
	ds_read_b32 v1, v1
	s_add_i32 s0, 0, 0x23f64
	v_mov_b32_e32 v2, s0
	ds_read_b32 v2, v2
	s_waitcnt lgkmcnt(1)
	v_cmp_ne_u32_e32 vcc, 0, v1
	s_cbranch_vccnz .LBB0_595
	s_add_u32 s12, s34, 0x4200
	s_addc_u32 s13, s35, 0
	s_add_u32 s14, s34, 0x4400
	s_addc_u32 s15, s35, 0
	s_add_u32 s16, s34, 0x4500
	s_addc_u32 s17, s35, 0
	s_add_u32 s18, s34, 0x4600
	s_addc_u32 s19, s35, 0
	s_add_u32 s20, s34, 0x4700
	s_addc_u32 s21, s35, 0
	s_add_u32 s22, s34, 0x4800
	s_addc_u32 s23, s35, 0
	s_add_u32 s44, s34, 0x4900
	s_addc_u32 s45, s35, 0
	s_add_u32 s46, s34, 0x4a00
	s_addc_u32 s47, s35, 0
	s_add_u32 s52, s34, 0x4b00
	s_addc_u32 s53, s35, 0
	s_add_u32 s54, s34, 0x4c00
	s_addc_u32 s55, s35, 0
	s_add_u32 s56, s34, 0x4d00
	s_addc_u32 s57, s35, 0
	s_add_u32 s58, s34, 0x4e00
	s_addc_u32 s59, s35, 0
	s_add_u32 s60, s34, 0x4f00
	v_readlane_b32 s4, v252, 0
	s_addc_u32 s61, s35, 0
	v_readlane_b32 s5, v252, 1
	s_add_u32 s62, s34, 0x5000
	s_load_dwordx2 s[0:1], s[4:5], 0x4
	s_addc_u32 s63, s35, 0
	s_add_u32 s64, s34, 0x5100
	s_addc_u32 s65, s35, 0
	s_add_u32 s66, s34, 0x5200
	s_addc_u32 s67, s35, 0
	s_waitcnt lgkmcnt(0)
	s_mul_i32 s0, s0, s33
	s_add_u32 s74, s34, 0x5300
	s_mul_i32 s0, s0, s1
	s_addc_u32 s75, s35, 0
	s_mov_b32 s1, 1
	v_mov_b32_e32 v17, 0
	s_branch .LBB0_583

; __device__ __forceinline__ unsigned xb_ld(unsigned* p)              { return __hip_atomic_load(p, __ATOMIC_RELAXED, __HIP_MEMORY_SCOPE_AGENT); }
;     ...
;         gen_ = __builtin_amdgcn_readfirstlane(gen_);
;         const bool act_ = (l_ < 16) && (xb_ld(&bar[XB_XCNT(l_ & 15)]) > 0u);
.LBB0_600:
	s_or_b64 exec, exec, s[10:11]
	v_cmp_gt_i32_e32 vcc, 16, v0
	v_lshlrev_b32_e32 v0, 6, v0
	v_and_b32_e32 v0, 0x3c0, v0
	v_readfirstlane_b32 s0, v2
	v_mov_b32_e32 v1, 0
	s_mov_b64 s[10:11], 0
	v_lshlrev_b32_e32 v0, 2, v0
	s_mov_b64 s[12:13], 0
	s_and_saveexec_b64 s[14:15], vcc
	s_cbranch_execz .LBB0_602
	s_waitcnt vmcnt(0)
	v_mov_b32_e32 v2, v30
	v_cmp_ne_u32_e32 vcc, 0, v2
	s_and_b64 s[12:13], vcc, exec

; __device__ __forceinline__ int lane_id() { return (int)__builtin_amdgcn_mbcnt_hi(~0u, __builtin_amdgcn_mbcnt_lo(~0u, 0u)); }
; __device__ __forceinline__ unsigned xb_ld(unsigned* p)              { return __hip_atomic_load(p, __ATOMIC_RELAXED, __HIP_MEMORY_SCOPE_AGENT); }
; __device__ __forceinline__ unsigned xb_add(unsigned* p, unsigned v) { return __hip_atomic_fetch_add(p, v, __ATOMIC_RELAXED, __HIP_MEMORY_SCOPE_AGENT); }
;     ...
;     if (b.wave == 0) {
;         unsigned* bar = b.bar; const int l_ = lane_id(); unsigned gen_ = 0u;
;         if (l_ == 0) {
;             __builtin_amdgcn_s_waitcnt(0);
;             unsigned nloc = b.st[0], nx = b.st[1];
;             if (nloc == 0u) { xcd_barrier_complete(bar, b.x, nloc, nx); b.st[0] = nloc; b.st[1] = nx; }
;             const unsigned old = xb_add(&bar[XB_XSUB(b.x)], 1u);
;             gen_ = old / nloc;
;             if (old + 1u == (gen_ + 1u) * nloc) {
;                 if (!wt_only) __builtin_amdgcn_fence(__ATOMIC_RELEASE, "agent");
;                 asm volatile("s_waitcnt vmcnt(0)" ::: "memory");
;                 __hip_atomic_store(&bar[XB_XGEN(b.x)], gen_ + 1u, __ATOMIC_RELAXED, __HIP_MEMORY_SCOPE_AGENT);
;             }
;         }
;         gen_ = __builtin_amdgcn_readfirstlane(gen_);
;         const bool act_ = (l_ < 16) && (xb_ld(&bar[XB_XCNT(l_ & 15)]) > 0u);
.LBB0_715:
	v_readlane_b32 s4, v252, 36
	v_readlane_b32 s5, v252, 37
	s_and_b64 vcc, exec, s[4:5]
	s_cbranch_vccnz .LBB0_753
	v_mbcnt_lo_u32_b32 v0, -1, 0
	v_mbcnt_hi_u32_b32 v0, -1, v0
	v_and_b32_e32 v31, 15, v0
	v_lshlrev_b32_e32 v31, 8, v31
	global_load_dword v30, v31, s[94:95] offset:1024 sc1
	v_mov_b32_e32 v2, 0
	v_cmp_ne_u32_e64 s[8:9], 0, v0
	v_cmp_eq_u32_e32 vcc, 0, v0
	s_and_saveexec_b64 s[12:13], vcc
	s_cbranch_execz .LBB0_737
	s_add_i32 s4, 0, 0x23f60
	v_mov_b32_e32 v1, s4
	s_waitcnt vmcnt(1) expcnt(0) lgkmcnt(0)
	ds_read_b32 v1, v1
	s_add_i32 s4, 0, 0x23f64
	v_mov_b32_e32 v2, s4
	ds_read_b32 v2, v2
	s_waitcnt lgkmcnt(1)
	v_cmp_ne_u32_e32 vcc, 0, v1
	s_cbranch_vccnz .LBB0_732
	s_add_u32 s14, s34, 0x4200
	s_addc_u32 s15, s35, 0
	s_add_u32 s16, s34, 0x4400
	s_addc_u32 s17, s35, 0
	s_add_u32 s18, s34, 0x4500
	s_addc_u32 s19, s35, 0
	s_add_u32 s20, s34, 0x4600
	s_addc_u32 s21, s35, 0
	s_add_u32 s22, s34, 0x4700
	s_addc_u32 s23, s35, 0
	s_add_u32 s24, s34, 0x4800
	s_addc_u32 s25, s35, 0
	s_add_u32 s44, s34, 0x4900
	s_addc_u32 s45, s35, 0
	s_add_u32 s46, s34, 0x4a00
	s_addc_u32 s47, s35, 0
	s_add_u32 s52, s34, 0x4b00
	s_addc_u32 s53, s35, 0
	s_add_u32 s54, s34, 0x4c00
	s_addc_u32 s55, s35, 0
	s_add_u32 s56, s34, 0x4d00
	s_addc_u32 s57, s35, 0
	s_add_u32 s58, s34, 0x4e00
	s_addc_u32 s59, s35, 0
	s_add_u32 s60, s34, 0x4f00
	v_readlane_b32 s6, v252, 0
	s_addc_u32 s61, s35, 0
	v_readlane_b32 s7, v252, 1
	s_add_u32 s62, s34, 0x5000
	s_load_dwordx2 s[4:5], s[6:7], 0x4
	s_addc_u32 s63, s35, 0
	s_add_u32 s64, s34, 0x5100
	s_addc_u32 s65, s35, 0
	s_add_u32 s66, s34, 0x5200
	s_addc_u32 s67, s35, 0
	s_waitcnt lgkmcnt(0)
	s_mul_i32 s4, s4, s33
	s_add_u32 s74, s34, 0x5300
	s_mul_i32 s4, s4, s5
	s_addc_u32 s75, s35, 0
	s_mov_b32 s5, 1
	v_mov_b32_e32 v17, 0
	s_branch .LBB0_720

; __device__ __forceinline__ unsigned xb_ld(unsigned* p)              { return __hip_atomic_load(p, __ATOMIC_RELAXED, __HIP_MEMORY_SCOPE_AGENT); }
;     ...
;         gen_ = __builtin_amdgcn_readfirstlane(gen_);
;         const bool act_ = (l_ < 16) && (xb_ld(&bar[XB_XCNT(l_ & 15)]) > 0u);
.LBB0_737:
	s_or_b64 exec, exec, s[12:13]
	v_cmp_gt_i32_e32 vcc, 16, v0
	v_lshlrev_b32_e32 v0, 6, v0
	v_and_b32_e32 v0, 0x3c0, v0
	v_readfirstlane_b32 s4, v2
	v_mov_b32_e32 v1, 0
	s_mov_b64 s[12:13], 0
	v_lshlrev_b32_e32 v0, 2, v0
	s_mov_b64 s[14:15], 0
	s_and_saveexec_b64 s[16:17], vcc
	s_cbranch_execz .LBB0_739
	s_waitcnt vmcnt(0)
	v_mov_b32_e32 v2, v30
	v_cmp_ne_u32_e32 vcc, 0, v2
	s_and_b64 s[14:15], vcc, exec

; __device__ __forceinline__ int lane_id() { return (int)__builtin_amdgcn_mbcnt_hi(~0u, __builtin_amdgcn_mbcnt_lo(~0u, 0u)); }
; __device__ __forceinline__ unsigned xb_ld(unsigned* p)              { return __hip_atomic_load(p, __ATOMIC_RELAXED, __HIP_MEMORY_SCOPE_AGENT); }
; __device__ __forceinline__ unsigned xb_add(unsigned* p, unsigned v) { return __hip_atomic_fetch_add(p, v, __ATOMIC_RELAXED, __HIP_MEMORY_SCOPE_AGENT); }
;     ...
;     if (b.wave == 0) {
;         unsigned* bar = b.bar; const int l_ = lane_id(); unsigned gen_ = 0u;
;         if (l_ == 0) {
;             __builtin_amdgcn_s_waitcnt(0);
;             unsigned nloc = b.st[0], nx = b.st[1];
;             if (nloc == 0u) { xcd_barrier_complete(bar, b.x, nloc, nx); b.st[0] = nloc; b.st[1] = nx; }
;             const unsigned old = xb_add(&bar[XB_XSUB(b.x)], 1u);
;             gen_ = old / nloc;
;             if (old + 1u == (gen_ + 1u) * nloc) {
;                 if (!wt_only) __builtin_amdgcn_fence(__ATOMIC_RELEASE, "agent");
;                 asm volatile("s_waitcnt vmcnt(0)" ::: "memory");
;                 __hip_atomic_store(&bar[XB_XGEN(b.x)], gen_ + 1u, __ATOMIC_RELAXED, __HIP_MEMORY_SCOPE_AGENT);
;             }
;         }
;         gen_ = __builtin_amdgcn_readfirstlane(gen_);
;         const bool act_ = (l_ < 16) && (xb_ld(&bar[XB_XCNT(l_ & 15)]) > 0u);
.LBB0_775:
	v_readlane_b32 s0, v252, 36
	v_readlane_b32 s1, v252, 37
	s_and_b64 vcc, exec, s[0:1]
	s_cbranch_vccnz .LBB0_813
	v_mbcnt_lo_u32_b32 v0, -1, 0
	v_mbcnt_hi_u32_b32 v0, -1, v0
	v_and_b32_e32 v31, 15, v0
	v_lshlrev_b32_e32 v31, 8, v31
	global_load_dword v30, v31, s[94:95] offset:1024 sc1
	v_mov_b32_e32 v2, 0
	v_cmp_ne_u32_e64 s[8:9], 0, v0
	v_cmp_eq_u32_e32 vcc, 0, v0
	s_and_saveexec_b64 s[10:11], vcc
	s_cbranch_execz .LBB0_797
	s_add_i32 s0, 0, 0x23f60
	v_mov_b32_e32 v1, s0
	s_waitcnt vmcnt(1) expcnt(0) lgkmcnt(0)
	ds_read_b32 v1, v1
	s_add_i32 s0, 0, 0x23f64
	v_mov_b32_e32 v2, s0
	ds_read_b32 v2, v2
	s_waitcnt lgkmcnt(1)
	v_cmp_ne_u32_e32 vcc, 0, v1
	s_cbranch_vccnz .LBB0_792
	s_add_u32 s12, s34, 0x4200
	s_addc_u32 s13, s35, 0
	s_add_u32 s14, s34, 0x4400
	s_addc_u32 s15, s35, 0
	s_add_u32 s16, s34, 0x4500
	s_addc_u32 s17, s35, 0
	s_add_u32 s18, s34, 0x4600
	s_addc_u32 s19, s35, 0
	s_add_u32 s20, s34, 0x4700
	s_addc_u32 s21, s35, 0
	s_add_u32 s22, s34, 0x4800
	s_addc_u32 s23, s35, 0
	s_add_u32 s24, s34, 0x4900
	s_addc_u32 s25, s35, 0
	s_add_u32 s44, s34, 0x4a00
	s_addc_u32 s45, s35, 0
	s_add_u32 s46, s34, 0x4b00
	s_addc_u32 s47, s35, 0
	s_add_u32 s52, s34, 0x4c00
	s_addc_u32 s53, s35, 0
	s_add_u32 s54, s34, 0x4d00
	s_addc_u32 s55, s35, 0
	s_add_u32 s56, s34, 0x4e00
	s_addc_u32 s57, s35, 0
	s_add_u32 s58, s34, 0x4f00
	v_readlane_b32 s4, v252, 0
	s_addc_u32 s59, s35, 0
	v_readlane_b32 s5, v252, 1
	s_add_u32 s60, s34, 0x5000
	s_load_dwordx2 s[0:1], s[4:5], 0x4
	s_addc_u32 s61, s35, 0
	s_add_u32 s62, s34, 0x5100
	s_addc_u32 s63, s35, 0
	s_add_u32 s64, s34, 0x5200
	s_addc_u32 s65, s35, 0
	s_waitcnt lgkmcnt(0)
	s_mul_i32 s0, s0, s33
	s_add_u32 s66, s34, 0x5300
	s_mul_i32 s0, s0, s1
	s_addc_u32 s67, s35, 0
	s_mov_b32 s1, 1
	v_mov_b32_e32 v17, 0
	s_branch .LBB0_780

; __device__ __forceinline__ int lane_id() { return (int)__builtin_amdgcn_mbcnt_hi(~0u, __builtin_amdgcn_mbcnt_lo(~0u, 0u)); }
; __device__ __forceinline__ unsigned xb_ld(unsigned* p)              { return __hip_atomic_load(p, __ATOMIC_RELAXED, __HIP_MEMORY_SCOPE_AGENT); }
; __device__ __forceinline__ unsigned xb_add(unsigned* p, unsigned v) { return __hip_atomic_fetch_add(p, v, __ATOMIC_RELAXED, __HIP_MEMORY_SCOPE_AGENT); }
;     ...
;     if (b.wave == 0) {
;         unsigned* bar = b.bar; const int l_ = lane_id(); unsigned gen_ = 0u;
;         if (l_ == 0) {
;             __builtin_amdgcn_s_waitcnt(0);
;             unsigned nloc = b.st[0], nx = b.st[1];
;             if (nloc == 0u) { xcd_barrier_complete(bar, b.x, nloc, nx); b.st[0] = nloc; b.st[1] = nx; }
;             const unsigned old = xb_add(&bar[XB_XSUB(b.x)], 1u);
;             gen_ = old / nloc;
;             if (old + 1u == (gen_ + 1u) * nloc) {
;                 if (!wt_only) __builtin_amdgcn_fence(__ATOMIC_RELEASE, "agent");
;                 asm volatile("s_waitcnt vmcnt(0)" ::: "memory");
;                 __hip_atomic_store(&bar[XB_XGEN(b.x)], gen_ + 1u, __ATOMIC_RELAXED, __HIP_MEMORY_SCOPE_AGENT);
;             }
;         }
;         gen_ = __builtin_amdgcn_readfirstlane(gen_);
;         const bool act_ = (l_ < 16) && (xb_ld(&bar[XB_XCNT(l_ & 15)]) > 0u);
.LBB0_824:
	v_readlane_b32 s0, v252, 36
	v_readlane_b32 s1, v252, 37
	s_and_b64 vcc, exec, s[0:1]
	s_cbranch_vccnz .LBB0_862
	s_waitcnt vmcnt(11)
	v_mbcnt_lo_u32_b32 v0, -1, 0
	v_mbcnt_hi_u32_b32 v0, -1, v0
	v_and_b32_e32 v31, 15, v0
	v_lshlrev_b32_e32 v31, 8, v31
	global_load_dword v30, v31, s[94:95] offset:1024 sc1
	v_mov_b32_e32 v2, 0
	v_cmp_ne_u32_e64 s[10:11], 0, v0
	v_cmp_eq_u32_e32 vcc, 0, v0
	s_and_saveexec_b64 s[12:13], vcc
	s_cbranch_execz .LBB0_846
	s_add_i32 s0, 0, 0x23f60
	v_mov_b32_e32 v1, s0
	s_waitcnt vmcnt(1) expcnt(0) lgkmcnt(0)
	ds_read_b32 v1, v1
	s_add_i32 s0, 0, 0x23f64
	v_mov_b32_e32 v2, s0
	ds_read_b32 v2, v2
	s_waitcnt lgkmcnt(1)
	v_cmp_ne_u32_e32 vcc, 0, v1
	s_cbranch_vccnz .LBB0_841
	s_add_u32 s14, s34, 0x4200
	s_addc_u32 s15, s35, 0
	s_add_u32 s16, s34, 0x4400
	s_addc_u32 s17, s35, 0
	s_add_u32 s18, s34, 0x4500
	s_addc_u32 s19, s35, 0
	s_add_u32 s20, s34, 0x4600
	s_addc_u32 s21, s35, 0
	s_add_u32 s22, s34, 0x4700
	s_addc_u32 s23, s35, 0
	s_add_u32 s24, s34, 0x4800
	s_addc_u32 s25, s35, 0
	s_add_u32 s30, s34, 0x4900
	s_addc_u32 s31, s35, 0
	s_add_u32 s36, s34, 0x4a00
	s_addc_u32 s37, s35, 0
	s_add_u32 s38, s34, 0x4b00
	s_addc_u32 s39, s35, 0
	s_add_u32 s44, s34, 0x4c00
	s_addc_u32 s45, s35, 0
	s_add_u32 s46, s34, 0x4d00
	s_addc_u32 s47, s35, 0
	s_add_u32 s52, s34, 0x4e00
	s_addc_u32 s53, s35, 0
	s_add_u32 s54, s34, 0x4f00
	v_readlane_b32 s4, v252, 0
	s_addc_u32 s55, s35, 0
	v_readlane_b32 s5, v252, 1
	s_add_u32 s56, s34, 0x5000
	s_load_dwordx2 s[0:1], s[4:5], 0x4
	s_addc_u32 s57, s35, 0
	s_add_u32 s58, s34, 0x5100
	s_addc_u32 s59, s35, 0
	s_add_u32 s60, s34, 0x5200
	s_addc_u32 s61, s35, 0
	s_waitcnt lgkmcnt(0)
	s_mul_i32 s0, s0, s33
	s_add_u32 s62, s34, 0x5300
	s_mul_i32 s0, s0, s1
	s_addc_u32 s63, s35, 0
	s_mov_b32 s1, 1
	v_mov_b32_e32 v17, 0
	s_branch .LBB0_829

; __device__ __forceinline__ unsigned xb_ld(unsigned* p)              { return __hip_atomic_load(p, __ATOMIC_RELAXED, __HIP_MEMORY_SCOPE_AGENT); }
;     ...
;         gen_ = __builtin_amdgcn_readfirstlane(gen_);
;         const bool act_ = (l_ < 16) && (xb_ld(&bar[XB_XCNT(l_ & 15)]) > 0u);
.LBB0_846:
	s_or_b64 exec, exec, s[12:13]
	v_cmp_gt_i32_e32 vcc, 16, v0
	v_lshlrev_b32_e32 v0, 6, v0
	v_and_b32_e32 v0, 0x3c0, v0
	v_readfirstlane_b32 s0, v2
	v_mov_b32_e32 v1, 0
	s_mov_b64 s[12:13], 0
	v_lshlrev_b32_e32 v0, 2, v0
	s_mov_b64 s[14:15], 0
	s_and_saveexec_b64 s[16:17], vcc
	s_cbranch_execz .LBB0_848
	s_waitcnt vmcnt(0)
	v_mov_b32_e32 v2, v30
	v_cmp_ne_u32_e32 vcc, 0, v2
	s_and_b64 s[14:15], vcc, exec

; __device__ __forceinline__ int lane_id() { return (int)__builtin_amdgcn_mbcnt_hi(~0u, __builtin_amdgcn_mbcnt_lo(~0u, 0u)); }
; __device__ __forceinline__ unsigned xb_ld(unsigned* p)              { return __hip_atomic_load(p, __ATOMIC_RELAXED, __HIP_MEMORY_SCOPE_AGENT); }
; __device__ __forceinline__ unsigned xb_add(unsigned* p, unsigned v) { return __hip_atomic_fetch_add(p, v, __ATOMIC_RELAXED, __HIP_MEMORY_SCOPE_AGENT); }
;     ...
;     if (b.wave == 0) {
;         unsigned* bar = b.bar; const int l_ = lane_id(); unsigned gen_ = 0u;
;         if (l_ == 0) {
;             __builtin_amdgcn_s_waitcnt(0);
;             unsigned nloc = b.st[0], nx = b.st[1];
;             if (nloc == 0u) { xcd_barrier_complete(bar, b.x, nloc, nx); b.st[0] = nloc; b.st[1] = nx; }
;             const unsigned old = xb_add(&bar[XB_XSUB(b.x)], 1u);
;             gen_ = old / nloc;
;             if (old + 1u == (gen_ + 1u) * nloc) {
;                 if (!wt_only) __builtin_amdgcn_fence(__ATOMIC_RELEASE, "agent");
;                 asm volatile("s_waitcnt vmcnt(0)" ::: "memory");
;                 __hip_atomic_store(&bar[XB_XGEN(b.x)], gen_ + 1u, __ATOMIC_RELAXED, __HIP_MEMORY_SCOPE_AGENT);
;             }
;         }
;         gen_ = __builtin_amdgcn_readfirstlane(gen_);
;         const bool act_ = (l_ < 16) && (xb_ld(&bar[XB_XCNT(l_ & 15)]) > 0u);
.LBB0_937:
	v_readlane_b32 s0, v252, 36
	v_readlane_b32 s1, v252, 37
	s_and_b64 vcc, exec, s[0:1]
	s_cbranch_vccnz .LBB0_975
	s_waitcnt vmcnt(11)
	v_mbcnt_lo_u32_b32 v0, -1, 0
	v_mbcnt_hi_u32_b32 v0, -1, v0
	v_and_b32_e32 v31, 15, v0
	v_lshlrev_b32_e32 v31, 8, v31
	global_load_dword v30, v31, s[94:95] offset:1024 sc1
	v_mov_b32_e32 v2, 0
	v_cmp_ne_u32_e64 s[10:11], 0, v0
	v_cmp_eq_u32_e32 vcc, 0, v0
	s_and_saveexec_b64 s[12:13], vcc
	s_cbranch_execz .LBB0_959
	s_add_i32 s0, 0, 0x23f60
	v_mov_b32_e32 v1, s0
	s_waitcnt vmcnt(1) expcnt(0) lgkmcnt(0)
	ds_read_b32 v1, v1
	s_add_i32 s0, 0, 0x23f64
	v_mov_b32_e32 v2, s0
	ds_read_b32 v2, v2
	s_waitcnt lgkmcnt(1)
	v_cmp_ne_u32_e32 vcc, 0, v1
	s_cbranch_vccnz .LBB0_954
	s_add_u32 s14, s34, 0x4200
	s_addc_u32 s15, s35, 0
	s_add_u32 s16, s34, 0x4400
	s_addc_u32 s17, s35, 0
	s_add_u32 s18, s34, 0x4500
	s_addc_u32 s19, s35, 0
	s_add_u32 s20, s34, 0x4600
	s_addc_u32 s21, s35, 0
	s_add_u32 s22, s34, 0x4700
	s_addc_u32 s23, s35, 0
	s_add_u32 s24, s34, 0x4800
	s_addc_u32 s25, s35, 0
	s_add_u32 s30, s34, 0x4900
	s_addc_u32 s31, s35, 0
	s_add_u32 s36, s34, 0x4a00
	s_addc_u32 s37, s35, 0
	s_add_u32 s38, s34, 0x4b00
	s_addc_u32 s39, s35, 0
	s_add_u32 s40, s34, 0x4c00
	s_addc_u32 s41, s35, 0
	s_add_u32 s44, s34, 0x4d00
	s_addc_u32 s45, s35, 0
	s_add_u32 s46, s34, 0x4e00
	s_addc_u32 s47, s35, 0
	s_add_u32 s52, s34, 0x4f00
	v_readlane_b32 s4, v252, 0
	s_addc_u32 s53, s35, 0
	v_readlane_b32 s5, v252, 1
	s_add_u32 s54, s34, 0x5000
	s_load_dwordx2 s[0:1], s[4:5], 0x4
	s_addc_u32 s55, s35, 0
	s_add_u32 s56, s34, 0x5100
	s_addc_u32 s57, s35, 0
	s_add_u32 s58, s34, 0x5200
	s_addc_u32 s59, s35, 0
	s_waitcnt lgkmcnt(0)
	s_mul_i32 s0, s0, s33
	s_add_u32 s60, s34, 0x5300
	s_mul_i32 s0, s0, s1
	s_addc_u32 s61, s35, 0
	s_mov_b32 s1, 1
	v_mov_b32_e32 v17, 0
	s_branch .LBB0_942

; __device__ __forceinline__ int lane_id() { return (int)__builtin_amdgcn_mbcnt_hi(~0u, __builtin_amdgcn_mbcnt_lo(~0u, 0u)); }
; __device__ __forceinline__ unsigned xb_ld(unsigned* p)              { return __hip_atomic_load(p, __ATOMIC_RELAXED, __HIP_MEMORY_SCOPE_AGENT); }
; __device__ __forceinline__ unsigned xb_add(unsigned* p, unsigned v) { return __hip_atomic_fetch_add(p, v, __ATOMIC_RELAXED, __HIP_MEMORY_SCOPE_AGENT); }
;     ...
;     if (b.wave == 0) {
;         unsigned* bar = b.bar; const int l_ = lane_id(); unsigned gen_ = 0u;
;         if (l_ == 0) {
;             __builtin_amdgcn_s_waitcnt(0);
;             unsigned nloc = b.st[0], nx = b.st[1];
;             if (nloc == 0u) { xcd_barrier_complete(bar, b.x, nloc, nx); b.st[0] = nloc; b.st[1] = nx; }
;             const unsigned old = xb_add(&bar[XB_XSUB(b.x)], 1u);
;             gen_ = old / nloc;
;             if (old + 1u == (gen_ + 1u) * nloc) {
;                 if (!wt_only) __builtin_amdgcn_fence(__ATOMIC_RELEASE, "agent");
;                 asm volatile("s_waitcnt vmcnt(0)" ::: "memory");
;                 __hip_atomic_store(&bar[XB_XGEN(b.x)], gen_ + 1u, __ATOMIC_RELAXED, __HIP_MEMORY_SCOPE_AGENT);
;             }
;         }
;         gen_ = __builtin_amdgcn_readfirstlane(gen_);
;         const bool act_ = (l_ < 16) && (xb_ld(&bar[XB_XCNT(l_ & 15)]) > 0u);
.LBB0_1079:
	v_readlane_b32 s4, v252, 36
	v_readlane_b32 s5, v252, 37
	s_and_b64 vcc, exec, s[4:5]
	s_cbranch_vccnz .LBB0_1117
	s_waitcnt vmcnt(11)
	v_mbcnt_lo_u32_b32 v0, -1, 0
	v_mbcnt_hi_u32_b32 v0, -1, v0
	v_and_b32_e32 v31, 15, v0
	v_lshlrev_b32_e32 v31, 8, v31
	global_load_dword v30, v31, s[94:95] offset:1024 sc1
	v_mov_b32_e32 v2, 0
	v_cmp_ne_u32_e64 s[10:11], 0, v0
	v_cmp_eq_u32_e32 vcc, 0, v0
	s_and_saveexec_b64 s[12:13], vcc
	s_cbranch_execz .LBB0_1101
	s_add_i32 s4, 0, 0x23f60
	v_mov_b32_e32 v1, s4
	s_waitcnt vmcnt(1) expcnt(0) lgkmcnt(0)
	ds_read_b32 v1, v1
	s_add_i32 s4, 0, 0x23f64
	v_mov_b32_e32 v2, s4
	ds_read_b32 v2, v2
	s_waitcnt lgkmcnt(1)
	v_cmp_ne_u32_e32 vcc, 0, v1
	s_cbranch_vccnz .LBB0_1096
	s_add_u32 s14, s34, 0x4200
	s_addc_u32 s15, s35, 0
	s_add_u32 s16, s34, 0x4400
	s_addc_u32 s17, s35, 0
	s_add_u32 s18, s34, 0x4500
	s_addc_u32 s19, s35, 0
	s_add_u32 s20, s34, 0x4600
	s_addc_u32 s21, s35, 0
	s_add_u32 s22, s34, 0x4700
	s_addc_u32 s23, s35, 0
	s_add_u32 s24, s34, 0x4800
	s_addc_u32 s25, s35, 0
	s_add_u32 s26, s34, 0x4900
	s_addc_u32 s27, s35, 0
	s_add_u32 s30, s34, 0x4a00
	s_addc_u32 s31, s35, 0
	s_add_u32 s36, s34, 0x4b00
	s_addc_u32 s37, s35, 0
	s_add_u32 s38, s34, 0x4c00
	s_addc_u32 s39, s35, 0
	s_add_u32 s40, s34, 0x4d00
	s_addc_u32 s41, s35, 0
	s_add_u32 s44, s34, 0x4e00
	s_addc_u32 s45, s35, 0
	s_add_u32 s46, s34, 0x4f00
	v_readlane_b32 s6, v252, 0
	s_addc_u32 s47, s35, 0
	v_readlane_b32 s7, v252, 1
	s_add_u32 s52, s34, 0x5000
	s_load_dwordx2 s[4:5], s[6:7], 0x4
	s_addc_u32 s53, s35, 0
	s_add_u32 s54, s34, 0x5100
	s_addc_u32 s55, s35, 0
	s_add_u32 s56, s34, 0x5200
	s_addc_u32 s57, s35, 0
	s_waitcnt lgkmcnt(0)
	s_mul_i32 s4, s4, s33
	s_add_u32 s58, s34, 0x5300
	s_mul_i32 s4, s4, s5
	s_addc_u32 s59, s35, 0
	s_mov_b32 s5, 1
	v_mov_b32_e32 v17, 0
	s_branch .LBB0_1084

; __device__ __forceinline__ int lane_id() { return (int)__builtin_amdgcn_mbcnt_hi(~0u, __builtin_amdgcn_mbcnt_lo(~0u, 0u)); }
; __device__ __forceinline__ unsigned xb_ld(unsigned* p)              { return __hip_atomic_load(p, __ATOMIC_RELAXED, __HIP_MEMORY_SCOPE_AGENT); }
; __device__ __forceinline__ unsigned xb_add(unsigned* p, unsigned v) { return __hip_atomic_fetch_add(p, v, __ATOMIC_RELAXED, __HIP_MEMORY_SCOPE_AGENT); }
;     ...
;     if (b.wave == 0) {
;         unsigned* bar = b.bar; const int l_ = lane_id(); unsigned gen_ = 0u;
;         if (l_ == 0) {
;             __builtin_amdgcn_s_waitcnt(0);
;             unsigned nloc = b.st[0], nx = b.st[1];
;             if (nloc == 0u) { xcd_barrier_complete(bar, b.x, nloc, nx); b.st[0] = nloc; b.st[1] = nx; }
;             const unsigned old = xb_add(&bar[XB_XSUB(b.x)], 1u);
;             gen_ = old / nloc;
;             if (old + 1u == (gen_ + 1u) * nloc) {
;                 if (!wt_only) __builtin_amdgcn_fence(__ATOMIC_RELEASE, "agent");
;                 asm volatile("s_waitcnt vmcnt(0)" ::: "memory");
;                 __hip_atomic_store(&bar[XB_XGEN(b.x)], gen_ + 1u, __ATOMIC_RELAXED, __HIP_MEMORY_SCOPE_AGENT);
;             }
;         }
;         gen_ = __builtin_amdgcn_readfirstlane(gen_);
;         const bool act_ = (l_ < 16) && (xb_ld(&bar[XB_XCNT(l_ & 15)]) > 0u);
.LBB0_1161:
	v_readlane_b32 s0, v252, 36
	v_readlane_b32 s1, v252, 37
	s_and_b64 vcc, exec, s[0:1]
	s_cbranch_vccnz .LBB0_1199
	v_mbcnt_lo_u32_b32 v0, -1, 0
	v_mbcnt_hi_u32_b32 v0, -1, v0
	v_and_b32_e32 v31, 15, v0
	v_lshlrev_b32_e32 v31, 8, v31
	global_load_dword v30, v31, s[94:95] offset:1024 sc1
	v_mov_b32_e32 v2, 0
	v_cmp_ne_u32_e64 s[0:1], 0, v0
	v_cmp_eq_u32_e32 vcc, 0, v0
	s_and_saveexec_b64 s[4:5], vcc
	s_cbranch_execz .LBB0_1183
	s_add_i32 s6, 0, 0x23f60
	v_mov_b32_e32 v1, s6
	s_waitcnt vmcnt(1) expcnt(0) lgkmcnt(0)
	ds_read_b32 v1, v1
	s_add_i32 s6, 0, 0x23f64
	v_mov_b32_e32 v2, s6
	ds_read_b32 v2, v2
	s_waitcnt lgkmcnt(1)
	v_cmp_ne_u32_e32 vcc, 0, v1
	s_cbranch_vccnz .LBB0_1178
	v_readlane_b32 s6, v252, 0
	v_readlane_b32 s7, v252, 1
	s_load_dwordx2 s[12:13], s[6:7], 0x4
	s_add_u32 s6, s34, 0x4200
	s_addc_u32 s7, s35, 0
	s_add_u32 s10, s34, 0x4400
	s_addc_u32 s11, s35, 0
	s_waitcnt lgkmcnt(0)
	s_mul_i32 s48, s12, s33
	s_add_u32 s12, s34, 0x4500
	s_mul_i32 s48, s48, s13
	s_addc_u32 s13, s35, 0
	s_add_u32 s14, s34, 0x4600
	s_addc_u32 s15, s35, 0
	s_add_u32 s16, s34, 0x4700
	s_addc_u32 s17, s35, 0
	s_add_u32 s18, s34, 0x4800
	s_addc_u32 s19, s35, 0
	s_add_u32 s20, s34, 0x4900
	s_addc_u32 s21, s35, 0
	s_add_u32 s22, s34, 0x4a00
	s_addc_u32 s23, s35, 0
	s_add_u32 s24, s34, 0x4b00
	s_addc_u32 s25, s35, 0
	s_add_u32 s26, s34, 0x4c00
	s_addc_u32 s27, s35, 0
	s_add_u32 s28, s34, 0x4d00
	s_addc_u32 s29, s35, 0
	s_add_u32 s30, s34, 0x4e00
	s_addc_u32 s31, s35, 0
	s_add_u32 s36, s34, 0x4f00
	s_addc_u32 s37, s35, 0
	s_add_u32 s38, s34, 0x5000
	s_addc_u32 s39, s35, 0
	s_add_u32 s40, s34, 0x5100
	s_addc_u32 s41, s35, 0
	s_add_u32 s42, s34, 0x5200
	s_addc_u32 s43, s35, 0
	s_add_u32 s44, s34, 0x5300
	s_addc_u32 s45, s35, 0
	s_mov_b32 s49, 1
	v_mov_b32_e32 v17, 0
	s_branch .LBB0_1166

; __device__ __forceinline__ unsigned xb_ld(unsigned* p)              { return __hip_atomic_load(p, __ATOMIC_RELAXED, __HIP_MEMORY_SCOPE_AGENT); }
;     ...
;         gen_ = __builtin_amdgcn_readfirstlane(gen_);
;         const bool act_ = (l_ < 16) && (xb_ld(&bar[XB_XCNT(l_ & 15)]) > 0u);
.LBB0_1183:
	s_or_b64 exec, exec, s[4:5]
	v_cmp_gt_i32_e32 vcc, 16, v0
	v_lshlrev_b32_e32 v0, 6, v0
	v_and_b32_e32 v0, 0x3c0, v0
	v_readfirstlane_b32 s20, v2
	v_mov_b32_e32 v1, 0
	s_mov_b64 s[4:5], 0
	v_lshlrev_b32_e32 v0, 2, v0
	s_mov_b64 s[6:7], 0
	s_and_saveexec_b64 s[10:11], vcc
	s_cbranch_execz .LBB0_1185
	s_waitcnt vmcnt(0)
	v_mov_b32_e32 v2, v30
	v_cmp_ne_u32_e32 vcc, 0, v2
	s_and_b64 s[6:7], vcc, exec
